# accumulate-chain MFMA ordering (k0,k1 of one accumulator back-to-back, SrcC forwarding) in 5 GEMM K-loops, on top of static leading-half priority
# speedup vs baseline: 1.0256x; 1.0076x over previous
.Lsp_LBB0269:
	s_or_b32 s54, s35, 1
	s_lshl_b64 s[16:17], s[54:55], 7
	s_add_i32 s54, s35, 2
	s_lshl_b64 s[44:45], s[54:55], 7
	s_add_u32 s46, s66, s44
	s_addc_u32 s47, s67, s45
	s_and_b64 vcc, s[14:15], exec
	s_cselect_b32 vcc_hi, s29, s47
	s_cselect_b32 vcc_lo, s65, s46
	s_add_u32 s44, s70, s44
	s_addc_u32 s45, s71, s45
	s_and_b64 s[14:15], s[14:15], exec
	s_cselect_b32 s15, s51, s45
	s_cselect_b32 s14, s30, s44
	s_add_i32 s44, 0, 0x10000
	v_add_u32_e32 v143, s44, v140
	s_add_i32 s45, 0, 0x14000
	ds_read_b128 v[136:139], v143
	ds_read_b128 v[144:147], v143 offset:1024
	ds_read_b128 v[148:151], v143 offset:2048
	ds_read_b128 v[152:155], v143 offset:3072
	v_add_u32_e32 v143, s45, v140
	ds_read_b128 v[168:171], v143
	ds_read_b128 v[172:175], v143 offset:1024
	ds_read_b128 v[176:179], v143 offset:2048
	ds_read_b128 v[180:183], v143 offset:3072
	s_add_u32 s16, s31, s16
	s_addc_u32 s17, s34, s17
	v_lshl_add_u64 v[156:157], s[16:17], 0, v[130:131]
	s_add_i32 m0, s73, 0xc000
	ds_read_b128 v[184:187], v142
	ds_read_b128 v[188:191], v142 offset:1024
	ds_read_b128 v[192:195], v142 offset:2048
	ds_read_b128 v[196:199], v142 offset:3072
	ds_read_b128 v[200:203], v142 offset:4096
	ds_read_b128 v[204:207], v142 offset:5120
	ds_read_b128 v[216:219], v142 offset:6144
	ds_read_b128 v[220:223], v142 offset:7168
	global_load_lds_dwordx4 v[156:157], off
	v_lshl_add_u64 v[156:157], s[16:17], 0, v[132:133]
	s_add_i32 m0, s73, 0xe000
	s_nop 0
	global_load_lds_dwordx4 v[156:157], off
	s_waitcnt vmcnt(8)
	s_waitcnt lgkmcnt(0)
	s_barrier
	s_waitcnt lgkmcnt(0)
	v_mfma_f32_16x16x32_bf16 v[122:125], v[136:139], v[184:187], v[122:125]
	v_mfma_f32_16x16x32_bf16 v[122:125], v[144:147], v[188:191], v[122:125]
	v_mfma_f32_16x16x32_bf16 v[114:117], v[148:151], v[184:187], v[114:117]
	v_mfma_f32_16x16x32_bf16 v[114:117], v[152:155], v[188:191], v[114:117]
	v_mfma_f32_16x16x32_bf16 v[106:109], v[136:139], v[192:195], v[106:109]
	v_mfma_f32_16x16x32_bf16 v[106:109], v[144:147], v[196:199], v[106:109]
	v_mfma_f32_16x16x32_bf16 v[102:105], v[148:151], v[192:195], v[102:105]
	v_mfma_f32_16x16x32_bf16 v[102:105], v[152:155], v[196:199], v[102:105]
	v_mfma_f32_16x16x32_bf16 v[90:93], v[136:139], v[200:203], v[90:93]
	v_mfma_f32_16x16x32_bf16 v[90:93], v[144:147], v[204:207], v[90:93]
	v_mfma_f32_16x16x32_bf16 v[86:89], v[148:151], v[200:203], v[86:89]
	v_mfma_f32_16x16x32_bf16 v[86:89], v[152:155], v[204:207], v[86:89]
	v_mfma_f32_16x16x32_bf16 v[74:77], v[136:139], v[216:219], v[74:77]
	v_mfma_f32_16x16x32_bf16 v[74:77], v[144:147], v[220:223], v[74:77]
	v_mfma_f32_16x16x32_bf16 v[70:73], v[148:151], v[216:219], v[70:73]
	v_mfma_f32_16x16x32_bf16 v[70:73], v[152:155], v[220:223], v[70:73]
	v_mfma_f32_16x16x32_bf16 v[126:129], v[168:171], v[184:187], v[126:129]
	v_mfma_f32_16x16x32_bf16 v[126:129], v[172:175], v[188:191], v[126:129]
	v_mfma_f32_16x16x32_bf16 v[118:121], v[176:179], v[184:187], v[118:121]
	v_mfma_f32_16x16x32_bf16 v[118:121], v[180:183], v[188:191], v[118:121]
	v_mfma_f32_16x16x32_bf16 v[110:113], v[168:171], v[192:195], v[110:113]
	v_mfma_f32_16x16x32_bf16 v[110:113], v[172:175], v[196:199], v[110:113]
	v_mfma_f32_16x16x32_bf16 v[98:101], v[176:179], v[192:195], v[98:101]
	v_mfma_f32_16x16x32_bf16 v[98:101], v[180:183], v[196:199], v[98:101]
	v_mfma_f32_16x16x32_bf16 v[94:97], v[168:171], v[200:203], v[94:97]
	v_mfma_f32_16x16x32_bf16 v[94:97], v[172:175], v[204:207], v[94:97]
	v_mfma_f32_16x16x32_bf16 v[82:85], v[176:179], v[200:203], v[82:85]
	v_mfma_f32_16x16x32_bf16 v[82:85], v[180:183], v[204:207], v[82:85]
	v_mfma_f32_16x16x32_bf16 v[78:81], v[168:171], v[216:219], v[78:81]
	v_mfma_f32_16x16x32_bf16 v[78:81], v[172:175], v[220:223], v[78:81]
	v_mfma_f32_16x16x32_bf16 v[66:69], v[176:179], v[216:219], v[66:69]
	v_mfma_f32_16x16x32_bf16 v[66:69], v[180:183], v[220:223], v[66:69]
	s_barrier
	s_add_i32 s16, s44, s61
	v_lshl_add_u64 v[156:157], s[14:15], 0, v[158:159]
	s_mov_b32 m0, s16
	ds_read_b128 v[184:187], v142 offset:16384
	ds_read_b128 v[188:191], v142 offset:17408
	ds_read_b128 v[192:195], v142 offset:18432
	ds_read_b128 v[196:199], v142 offset:19456
	ds_read_b128 v[200:203], v142 offset:20480
	ds_read_b128 v[204:207], v142 offset:21504
	ds_read_b128 v[216:219], v142 offset:22528
	ds_read_b128 v[220:223], v142 offset:23552
	global_load_lds_dwordx4 v[156:157], off
	s_add_i32 m0, s16, 0x2000
	s_add_u32 s16, s14, 0x80000
	v_lshl_add_u64 v[224:225], s[14:15], 0, v[134:135]
	s_addc_u32 s17, s15, 0
	s_add_i32 s44, s45, s61
	global_load_lds_dwordx4 v[224:225], off
	v_lshl_add_u64 v[226:227], s[16:17], 0, v[158:159]
	s_mov_b32 m0, s44
	v_lshl_add_u64 v[228:229], vcc, 0, v[132:133]
	global_load_lds_dwordx4 v[226:227], off
	v_lshl_add_u64 v[226:227], s[16:17], 0, v[134:135]
	s_add_i32 m0, s44, 0x2000
	s_nop 0
	global_load_lds_dwordx4 v[226:227], off
	v_lshl_add_u64 v[226:227], vcc, 0, v[130:131]
	s_mov_b32 m0, s73
	s_nop 0
	global_load_lds_dwordx4 v[226:227], off
	s_mov_b32 m0, s75
	s_nop 0
	global_load_lds_dwordx4 v[228:229], off
	s_waitcnt vmcnt(8)
	s_waitcnt lgkmcnt(0)
	s_barrier
	s_waitcnt lgkmcnt(0)
	v_mfma_f32_16x16x32_bf16 v[58:61], v[136:139], v[184:187], v[58:61]
	v_mfma_f32_16x16x32_bf16 v[58:61], v[144:147], v[188:191], v[58:61]
	v_mfma_f32_16x16x32_bf16 v[54:57], v[148:151], v[184:187], v[54:57]
	v_mfma_f32_16x16x32_bf16 v[54:57], v[152:155], v[188:191], v[54:57]
	v_mfma_f32_16x16x32_bf16 v[42:45], v[136:139], v[192:195], v[42:45]
	v_mfma_f32_16x16x32_bf16 v[42:45], v[144:147], v[196:199], v[42:45]
	v_mfma_f32_16x16x32_bf16 v[38:41], v[148:151], v[192:195], v[38:41]
	v_mfma_f32_16x16x32_bf16 v[38:41], v[152:155], v[196:199], v[38:41]
	v_mfma_f32_16x16x32_bf16 v[26:29], v[136:139], v[200:203], v[26:29]
	v_mfma_f32_16x16x32_bf16 v[26:29], v[144:147], v[204:207], v[26:29]
	v_mfma_f32_16x16x32_bf16 v[22:25], v[148:151], v[200:203], v[22:25]
	v_mfma_f32_16x16x32_bf16 v[22:25], v[152:155], v[204:207], v[22:25]
	v_mfma_f32_16x16x32_bf16 v[10:13], v[136:139], v[216:219], v[10:13]
	v_mfma_f32_16x16x32_bf16 v[10:13], v[144:147], v[220:223], v[10:13]
	v_mfma_f32_16x16x32_bf16 v[2:5], v[148:151], v[216:219], v[2:5]
	v_mfma_f32_16x16x32_bf16 v[2:5], v[152:155], v[220:223], v[2:5]
	v_mfma_f32_16x16x32_bf16 v[62:65], v[168:171], v[184:187], v[62:65]
	v_mfma_f32_16x16x32_bf16 v[62:65], v[172:175], v[188:191], v[62:65]
	v_mfma_f32_16x16x32_bf16 v[50:53], v[176:179], v[184:187], v[50:53]
	v_mfma_f32_16x16x32_bf16 v[50:53], v[180:183], v[188:191], v[50:53]
	v_mfma_f32_16x16x32_bf16 v[46:49], v[168:171], v[192:195], v[46:49]
	v_mfma_f32_16x16x32_bf16 v[46:49], v[172:175], v[196:199], v[46:49]
	v_mfma_f32_16x16x32_bf16 v[34:37], v[176:179], v[192:195], v[34:37]
	v_mfma_f32_16x16x32_bf16 v[34:37], v[180:183], v[196:199], v[34:37]
	v_mfma_f32_16x16x32_bf16 v[30:33], v[168:171], v[200:203], v[30:33]
	v_mfma_f32_16x16x32_bf16 v[30:33], v[172:175], v[204:207], v[30:33]
	v_mfma_f32_16x16x32_bf16 v[18:21], v[176:179], v[200:203], v[18:21]
	v_mfma_f32_16x16x32_bf16 v[18:21], v[180:183], v[204:207], v[18:21]
	v_mfma_f32_16x16x32_bf16 v[14:17], v[168:171], v[216:219], v[14:17]
	v_mfma_f32_16x16x32_bf16 v[14:17], v[172:175], v[220:223], v[14:17]
	v_mfma_f32_16x16x32_bf16 v[6:9], v[176:179], v[216:219], v[6:9]
	v_mfma_f32_16x16x32_bf16 v[6:9], v[180:183], v[220:223], v[6:9]
	s_barrier
	s_add_i32 s44, 0, 0x18000
	v_add_u32_e32 v143, s44, v140
	s_add_i32 s45, 0, 0x1c000
	ds_read_b128 v[136:139], v143
	ds_read_b128 v[144:147], v143 offset:1024
	ds_read_b128 v[148:151], v143 offset:2048
	ds_read_b128 v[152:155], v143 offset:3072
	v_add_u32_e32 v143, s45, v140
	ds_read_b128 v[168:171], v143
	ds_read_b128 v[172:175], v143 offset:1024
	ds_read_b128 v[176:179], v143 offset:2048
	ds_read_b128 v[180:183], v143 offset:3072
	s_add_u32 s16, vcc_lo, 0x80000
	s_addc_u32 s17, vcc_hi, 0
	s_mov_b32 m0, s24
	v_lshl_add_u64 v[230:231], s[16:17], 0, v[130:131]
	ds_read_b128 v[184:187], v142 offset:32768
	ds_read_b128 v[188:191], v142 offset:33792
	ds_read_b128 v[192:195], v142 offset:34816
	ds_read_b128 v[196:199], v142 offset:35840
	ds_read_b128 v[200:203], v142 offset:36864
	ds_read_b128 v[204:207], v142 offset:37888
	ds_read_b128 v[216:219], v142 offset:38912
	ds_read_b128 v[220:223], v142 offset:39936
	global_load_lds_dwordx4 v[230:231], off
	v_lshl_add_u64 v[230:231], s[16:17], 0, v[132:133]
	s_mov_b32 m0, s25
	s_nop 0
	global_load_lds_dwordx4 v[230:231], off
	s_waitcnt vmcnt(8)
	s_waitcnt lgkmcnt(0)
	s_barrier
	s_waitcnt lgkmcnt(0)
	v_mfma_f32_16x16x32_bf16 v[122:125], v[136:139], v[184:187], v[122:125]
	v_mfma_f32_16x16x32_bf16 v[122:125], v[144:147], v[188:191], v[122:125]
	v_mfma_f32_16x16x32_bf16 v[114:117], v[148:151], v[184:187], v[114:117]
	v_mfma_f32_16x16x32_bf16 v[114:117], v[152:155], v[188:191], v[114:117]
	v_mfma_f32_16x16x32_bf16 v[106:109], v[136:139], v[192:195], v[106:109]
	v_mfma_f32_16x16x32_bf16 v[106:109], v[144:147], v[196:199], v[106:109]
	v_mfma_f32_16x16x32_bf16 v[102:105], v[148:151], v[192:195], v[102:105]
	v_mfma_f32_16x16x32_bf16 v[102:105], v[152:155], v[196:199], v[102:105]
	v_mfma_f32_16x16x32_bf16 v[90:93], v[136:139], v[200:203], v[90:93]
	v_mfma_f32_16x16x32_bf16 v[90:93], v[144:147], v[204:207], v[90:93]
	v_mfma_f32_16x16x32_bf16 v[86:89], v[148:151], v[200:203], v[86:89]
	v_mfma_f32_16x16x32_bf16 v[86:89], v[152:155], v[204:207], v[86:89]
	v_mfma_f32_16x16x32_bf16 v[74:77], v[136:139], v[216:219], v[74:77]
	v_mfma_f32_16x16x32_bf16 v[74:77], v[144:147], v[220:223], v[74:77]
	v_mfma_f32_16x16x32_bf16 v[70:73], v[148:151], v[216:219], v[70:73]
	v_mfma_f32_16x16x32_bf16 v[70:73], v[152:155], v[220:223], v[70:73]
	v_mfma_f32_16x16x32_bf16 v[126:129], v[168:171], v[184:187], v[126:129]
	v_mfma_f32_16x16x32_bf16 v[126:129], v[172:175], v[188:191], v[126:129]
	v_mfma_f32_16x16x32_bf16 v[118:121], v[176:179], v[184:187], v[118:121]
	v_mfma_f32_16x16x32_bf16 v[118:121], v[180:183], v[188:191], v[118:121]
	v_mfma_f32_16x16x32_bf16 v[110:113], v[168:171], v[192:195], v[110:113]
	v_mfma_f32_16x16x32_bf16 v[110:113], v[172:175], v[196:199], v[110:113]
	v_mfma_f32_16x16x32_bf16 v[98:101], v[176:179], v[192:195], v[98:101]
	v_mfma_f32_16x16x32_bf16 v[98:101], v[180:183], v[196:199], v[98:101]
	v_mfma_f32_16x16x32_bf16 v[94:97], v[168:171], v[200:203], v[94:97]
	v_mfma_f32_16x16x32_bf16 v[94:97], v[172:175], v[204:207], v[94:97]
	v_mfma_f32_16x16x32_bf16 v[82:85], v[176:179], v[200:203], v[82:85]
	v_mfma_f32_16x16x32_bf16 v[82:85], v[180:183], v[204:207], v[82:85]
	v_mfma_f32_16x16x32_bf16 v[78:81], v[168:171], v[216:219], v[78:81]
	v_mfma_f32_16x16x32_bf16 v[78:81], v[172:175], v[220:223], v[78:81]
	v_mfma_f32_16x16x32_bf16 v[66:69], v[176:179], v[216:219], v[66:69]
	v_mfma_f32_16x16x32_bf16 v[66:69], v[180:183], v[220:223], v[66:69]
	s_barrier
	s_add_i32 s16, s44, s61
	v_lshl_add_u64 v[156:157], v[156:157], 0, s[56:57]
	s_mov_b32 m0, s16
	ds_read_b128 v[184:187], v142 offset:49152
	ds_read_b128 v[188:191], v142 offset:50176
	ds_read_b128 v[192:195], v142 offset:51200
	ds_read_b128 v[196:199], v142 offset:52224
	ds_read_b128 v[200:203], v142 offset:53248
	ds_read_b128 v[204:207], v142 offset:54272
	ds_read_b128 v[216:219], v142 offset:55296
	ds_read_b128 v[220:223], v142 offset:56320
	global_load_lds_dwordx4 v[156:157], off
	s_add_i32 m0, s16, 0x2000
	s_add_u32 s14, s14, 0x80080
	v_lshl_add_u64 v[156:157], v[224:225], 0, s[56:57]
	s_addc_u32 s15, s15, 0
	s_add_i32 s16, s45, s61
	global_load_lds_dwordx4 v[156:157], off
	v_lshl_add_u64 v[156:157], s[14:15], 0, v[158:159]
	s_mov_b32 m0, s16
	s_nop 0
	global_load_lds_dwordx4 v[156:157], off
	v_lshl_add_u64 v[156:157], s[14:15], 0, v[134:135]
	s_add_i32 m0, s16, 0x2000
	s_nop 0
	global_load_lds_dwordx4 v[156:157], off
	v_lshl_add_u64 v[156:157], v[226:227], 0, s[56:57]
	s_mov_b32 m0, s26
	s_nop 0
	global_load_lds_dwordx4 v[156:157], off
	v_lshl_add_u64 v[156:157], v[228:229], 0, s[56:57]
	s_mov_b32 m0, s27
	s_nop 0
	global_load_lds_dwordx4 v[156:157], off
	s_waitcnt vmcnt(8)
	s_waitcnt lgkmcnt(0)
	s_barrier
	s_waitcnt lgkmcnt(0)
	v_mfma_f32_16x16x32_bf16 v[58:61], v[136:139], v[184:187], v[58:61]
	v_mfma_f32_16x16x32_bf16 v[58:61], v[144:147], v[188:191], v[58:61]
	v_mfma_f32_16x16x32_bf16 v[54:57], v[148:151], v[184:187], v[54:57]
	v_mfma_f32_16x16x32_bf16 v[54:57], v[152:155], v[188:191], v[54:57]
	v_mfma_f32_16x16x32_bf16 v[42:45], v[136:139], v[192:195], v[42:45]
	v_mfma_f32_16x16x32_bf16 v[42:45], v[144:147], v[196:199], v[42:45]
	v_mfma_f32_16x16x32_bf16 v[38:41], v[148:151], v[192:195], v[38:41]
	v_mfma_f32_16x16x32_bf16 v[38:41], v[152:155], v[196:199], v[38:41]
	v_mfma_f32_16x16x32_bf16 v[26:29], v[136:139], v[200:203], v[26:29]
	v_mfma_f32_16x16x32_bf16 v[26:29], v[144:147], v[204:207], v[26:29]
	v_mfma_f32_16x16x32_bf16 v[22:25], v[148:151], v[200:203], v[22:25]
	v_mfma_f32_16x16x32_bf16 v[22:25], v[152:155], v[204:207], v[22:25]
	v_mfma_f32_16x16x32_bf16 v[10:13], v[136:139], v[216:219], v[10:13]
	v_mfma_f32_16x16x32_bf16 v[10:13], v[144:147], v[220:223], v[10:13]
	v_mfma_f32_16x16x32_bf16 v[2:5], v[148:151], v[216:219], v[2:5]
	v_mfma_f32_16x16x32_bf16 v[2:5], v[152:155], v[220:223], v[2:5]
	v_mfma_f32_16x16x32_bf16 v[62:65], v[168:171], v[184:187], v[62:65]
	v_mfma_f32_16x16x32_bf16 v[62:65], v[172:175], v[188:191], v[62:65]
	v_mfma_f32_16x16x32_bf16 v[50:53], v[176:179], v[184:187], v[50:53]
	v_mfma_f32_16x16x32_bf16 v[50:53], v[180:183], v[188:191], v[50:53]
	v_mfma_f32_16x16x32_bf16 v[46:49], v[168:171], v[192:195], v[46:49]
	v_mfma_f32_16x16x32_bf16 v[46:49], v[172:175], v[196:199], v[46:49]
	v_mfma_f32_16x16x32_bf16 v[34:37], v[176:179], v[192:195], v[34:37]
	v_mfma_f32_16x16x32_bf16 v[34:37], v[180:183], v[196:199], v[34:37]
	v_mfma_f32_16x16x32_bf16 v[30:33], v[168:171], v[200:203], v[30:33]
	v_mfma_f32_16x16x32_bf16 v[30:33], v[172:175], v[204:207], v[30:33]
	v_mfma_f32_16x16x32_bf16 v[18:21], v[176:179], v[200:203], v[18:21]
	v_mfma_f32_16x16x32_bf16 v[18:21], v[180:183], v[204:207], v[18:21]
	v_mfma_f32_16x16x32_bf16 v[14:17], v[168:171], v[216:219], v[14:17]
	v_mfma_f32_16x16x32_bf16 v[14:17], v[172:175], v[220:223], v[14:17]
	v_mfma_f32_16x16x32_bf16 v[6:9], v[176:179], v[216:219], v[6:9]
	v_mfma_f32_16x16x32_bf16 v[6:9], v[180:183], v[220:223], v[6:9]
	s_barrier
	s_cmp_gt_u32 s35, 29
	s_mov_b32 s35, s54
	s_cbranch_scc1 .LBB0_279

.Lsp_LBB0353:
	s_add_u32 s36, s0, 0x100
	s_addc_u32 s37, s1, 0
	s_add_i32 s27, 0, 0x10000
	s_cmpk_eq_i32 s26, 0x52
	s_cselect_b32 s69, s65, s37
	s_cselect_b32 s68, s64, s36
	v_add_u32_e32 v144, s27, v146
	s_cselect_b32 s15, s67, s25
	s_cselect_b32 s14, s66, s24
	s_add_i32 s28, 0, 0x14000
	ds_read_b128 v[140:143], v144
	ds_read_b128 v[150:153], v144 offset:1024
	ds_read_b128 v[154:157], v144 offset:2048
	ds_read_b128 v[168:171], v144 offset:3072
	v_add_u32_e32 v144, s28, v146
	ds_read_b128 v[172:175], v144
	ds_read_b128 v[176:179], v144 offset:1024
	ds_read_b128 v[180:183], v144 offset:2048
	ds_read_b128 v[184:187], v144 offset:3072
	v_lshl_add_u64 v[144:145], s[0:1], 0, v[136:137]
	s_add_i32 m0, s59, 0xc000
	ds_read_b128 v[188:191], v148
	ds_read_b128 v[192:195], v148 offset:1024
	ds_read_b128 v[196:199], v148 offset:2048
	ds_read_b128 v[200:203], v148 offset:3072
	ds_read_b128 v[204:207], v148 offset:4096
	ds_read_b128 v[216:219], v148 offset:5120
	ds_read_b128 v[220:223], v148 offset:6144
	ds_read_b128 v[224:227], v148 offset:7168
	global_load_lds_dwordx4 v[144:145], off
	v_lshl_add_u64 v[144:145], s[0:1], 0, v[138:139]
	s_add_i32 m0, s59, 0xe000
	s_nop 0
	global_load_lds_dwordx4 v[144:145], off
	s_waitcnt vmcnt(8)
	s_waitcnt lgkmcnt(0)
	s_barrier
	s_waitcnt lgkmcnt(0)
	v_mfma_f32_16x16x32_bf16 v[126:129], v[140:143], v[188:191], v[126:129]
	v_mfma_f32_16x16x32_bf16 v[126:129], v[150:153], v[192:195], v[126:129]
	v_mfma_f32_16x16x32_bf16 v[122:125], v[154:157], v[188:191], v[122:125]
	v_mfma_f32_16x16x32_bf16 v[122:125], v[168:171], v[192:195], v[122:125]
	v_mfma_f32_16x16x32_bf16 v[110:113], v[140:143], v[196:199], v[110:113]
	v_mfma_f32_16x16x32_bf16 v[110:113], v[150:153], v[200:203], v[110:113]
	v_mfma_f32_16x16x32_bf16 v[106:109], v[154:157], v[196:199], v[106:109]
	v_mfma_f32_16x16x32_bf16 v[106:109], v[168:171], v[200:203], v[106:109]
	v_mfma_f32_16x16x32_bf16 v[94:97], v[140:143], v[204:207], v[94:97]
	v_mfma_f32_16x16x32_bf16 v[94:97], v[150:153], v[216:219], v[94:97]
	v_mfma_f32_16x16x32_bf16 v[90:93], v[154:157], v[204:207], v[90:93]
	v_mfma_f32_16x16x32_bf16 v[90:93], v[168:171], v[216:219], v[90:93]
	v_mfma_f32_16x16x32_bf16 v[78:81], v[140:143], v[220:223], v[78:81]
	v_mfma_f32_16x16x32_bf16 v[78:81], v[150:153], v[224:227], v[78:81]
	v_mfma_f32_16x16x32_bf16 v[74:77], v[154:157], v[220:223], v[74:77]
	v_mfma_f32_16x16x32_bf16 v[74:77], v[168:171], v[224:227], v[74:77]
	v_mfma_f32_16x16x32_bf16 v[118:121], v[172:175], v[188:191], v[118:121]
	v_mfma_f32_16x16x32_bf16 v[118:121], v[176:179], v[192:195], v[118:121]
	v_mfma_f32_16x16x32_bf16 v[114:117], v[180:183], v[188:191], v[114:117]
	v_mfma_f32_16x16x32_bf16 v[114:117], v[184:187], v[192:195], v[114:117]
	v_mfma_f32_16x16x32_bf16 v[102:105], v[172:175], v[196:199], v[102:105]
	v_mfma_f32_16x16x32_bf16 v[102:105], v[176:179], v[200:203], v[102:105]
	v_mfma_f32_16x16x32_bf16 v[98:101], v[180:183], v[196:199], v[98:101]
	v_mfma_f32_16x16x32_bf16 v[98:101], v[184:187], v[200:203], v[98:101]
	v_mfma_f32_16x16x32_bf16 v[86:89], v[172:175], v[204:207], v[86:89]
	v_mfma_f32_16x16x32_bf16 v[86:89], v[176:179], v[216:219], v[86:89]
	v_mfma_f32_16x16x32_bf16 v[82:85], v[180:183], v[204:207], v[82:85]
	v_mfma_f32_16x16x32_bf16 v[82:85], v[184:187], v[216:219], v[82:85]
	v_mfma_f32_16x16x32_bf16 v[70:73], v[172:175], v[220:223], v[70:73]
	v_mfma_f32_16x16x32_bf16 v[70:73], v[176:179], v[224:227], v[70:73]
	v_mfma_f32_16x16x32_bf16 v[66:69], v[180:183], v[220:223], v[66:69]
	v_mfma_f32_16x16x32_bf16 v[66:69], v[184:187], v[224:227], v[66:69]
	s_barrier
	s_add_i32 s0, s27, s58
	v_lshl_add_u64 v[144:145], s[14:15], 0, v[158:159]
	s_mov_b32 m0, s0
	ds_read_b128 v[188:191], v148 offset:16384
	ds_read_b128 v[192:195], v148 offset:17408
	ds_read_b128 v[196:199], v148 offset:18432
	ds_read_b128 v[200:203], v148 offset:19456
	ds_read_b128 v[204:207], v148 offset:20480
	ds_read_b128 v[216:219], v148 offset:21504
	ds_read_b128 v[220:223], v148 offset:22528
	ds_read_b128 v[224:227], v148 offset:23552
	global_load_lds_dwordx4 v[144:145], off
	s_add_i32 m0, s0, 0x2000
	s_add_u32 s0, s14, 0x158000
	v_lshl_add_u64 v[228:229], s[14:15], 0, v[134:135]
	s_addc_u32 s1, s15, 0
	s_add_i32 s27, s28, s58
	global_load_lds_dwordx4 v[228:229], off
	v_lshl_add_u64 v[230:231], s[0:1], 0, v[158:159]
	s_mov_b32 m0, s27
	v_lshl_add_u64 v[232:233], s[68:69], 0, v[132:133]
	global_load_lds_dwordx4 v[230:231], off
	v_lshl_add_u64 v[230:231], s[0:1], 0, v[134:135]
	s_add_i32 m0, s27, 0x2000
	s_nop 0
	global_load_lds_dwordx4 v[230:231], off
	v_lshl_add_u64 v[230:231], s[68:69], 0, v[130:131]
	s_mov_b32 m0, s59
	s_nop 0
	global_load_lds_dwordx4 v[230:231], off
	s_mov_b32 m0, s70
	s_nop 0
	global_load_lds_dwordx4 v[232:233], off
	s_waitcnt vmcnt(8)
	s_waitcnt lgkmcnt(0)
	s_barrier
	s_waitcnt lgkmcnt(0)
	v_mfma_f32_16x16x32_bf16 v[62:65], v[140:143], v[188:191], v[62:65]
	v_mfma_f32_16x16x32_bf16 v[62:65], v[150:153], v[192:195], v[62:65]
	v_mfma_f32_16x16x32_bf16 v[58:61], v[154:157], v[188:191], v[58:61]
	v_mfma_f32_16x16x32_bf16 v[58:61], v[168:171], v[192:195], v[58:61]
	v_mfma_f32_16x16x32_bf16 v[46:49], v[140:143], v[196:199], v[46:49]
	v_mfma_f32_16x16x32_bf16 v[46:49], v[150:153], v[200:203], v[46:49]
	v_mfma_f32_16x16x32_bf16 v[42:45], v[154:157], v[196:199], v[42:45]
	v_mfma_f32_16x16x32_bf16 v[42:45], v[168:171], v[200:203], v[42:45]
	v_mfma_f32_16x16x32_bf16 v[30:33], v[140:143], v[204:207], v[30:33]
	v_mfma_f32_16x16x32_bf16 v[30:33], v[150:153], v[216:219], v[30:33]
	v_mfma_f32_16x16x32_bf16 v[26:29], v[154:157], v[204:207], v[26:29]
	v_mfma_f32_16x16x32_bf16 v[26:29], v[168:171], v[216:219], v[26:29]
	v_mfma_f32_16x16x32_bf16 v[14:17], v[140:143], v[220:223], v[14:17]
	v_mfma_f32_16x16x32_bf16 v[14:17], v[150:153], v[224:227], v[14:17]
	v_mfma_f32_16x16x32_bf16 v[10:13], v[154:157], v[220:223], v[10:13]
	v_mfma_f32_16x16x32_bf16 v[10:13], v[168:171], v[224:227], v[10:13]
	v_mfma_f32_16x16x32_bf16 v[54:57], v[172:175], v[188:191], v[54:57]
	v_mfma_f32_16x16x32_bf16 v[54:57], v[176:179], v[192:195], v[54:57]
	v_mfma_f32_16x16x32_bf16 v[50:53], v[180:183], v[188:191], v[50:53]
	v_mfma_f32_16x16x32_bf16 v[50:53], v[184:187], v[192:195], v[50:53]
	v_mfma_f32_16x16x32_bf16 v[38:41], v[172:175], v[196:199], v[38:41]
	v_mfma_f32_16x16x32_bf16 v[38:41], v[176:179], v[200:203], v[38:41]
	v_mfma_f32_16x16x32_bf16 v[34:37], v[180:183], v[196:199], v[34:37]
	v_mfma_f32_16x16x32_bf16 v[34:37], v[184:187], v[200:203], v[34:37]
	v_mfma_f32_16x16x32_bf16 v[22:25], v[172:175], v[204:207], v[22:25]
	v_mfma_f32_16x16x32_bf16 v[22:25], v[176:179], v[216:219], v[22:25]
	v_mfma_f32_16x16x32_bf16 v[18:21], v[180:183], v[204:207], v[18:21]
	v_mfma_f32_16x16x32_bf16 v[18:21], v[184:187], v[216:219], v[18:21]
	v_mfma_f32_16x16x32_bf16 v[6:9], v[172:175], v[220:223], v[6:9]
	v_mfma_f32_16x16x32_bf16 v[6:9], v[176:179], v[224:227], v[6:9]
	v_mfma_f32_16x16x32_bf16 v[2:5], v[180:183], v[220:223], v[2:5]
	v_mfma_f32_16x16x32_bf16 v[2:5], v[184:187], v[224:227], v[2:5]
	s_barrier
	s_add_i32 s27, 0, 0x18000
	v_add_u32_e32 v149, s27, v146
	s_add_i32 s28, 0, 0x1c000
	ds_read_b128 v[140:143], v149
	ds_read_b128 v[150:153], v149 offset:1024
	ds_read_b128 v[154:157], v149 offset:2048
	ds_read_b128 v[168:171], v149 offset:3072
	v_add_u32_e32 v149, s28, v146
	ds_read_b128 v[172:175], v149
	ds_read_b128 v[176:179], v149 offset:1024
	ds_read_b128 v[180:183], v149 offset:2048
	ds_read_b128 v[184:187], v149 offset:3072
	s_add_u32 s0, s68, 0x158000
	s_addc_u32 s1, s69, 0
	s_mov_b32 m0, s71
	v_lshl_add_u64 v[234:235], s[0:1], 0, v[130:131]
	ds_read_b128 v[188:191], v148 offset:32768
	ds_read_b128 v[192:195], v148 offset:33792
	ds_read_b128 v[196:199], v148 offset:34816
	ds_read_b128 v[200:203], v148 offset:35840
	ds_read_b128 v[204:207], v148 offset:36864
	ds_read_b128 v[216:219], v148 offset:37888
	ds_read_b128 v[220:223], v148 offset:38912
	ds_read_b128 v[224:227], v148 offset:39936
	global_load_lds_dwordx4 v[234:235], off
	v_lshl_add_u64 v[234:235], s[0:1], 0, v[132:133]
	s_mov_b32 m0, s72
	s_nop 0
	global_load_lds_dwordx4 v[234:235], off
	s_waitcnt vmcnt(8)
	s_waitcnt lgkmcnt(0)
	s_barrier
	s_waitcnt lgkmcnt(0)
	v_mfma_f32_16x16x32_bf16 v[126:129], v[140:143], v[188:191], v[126:129]
	v_mfma_f32_16x16x32_bf16 v[126:129], v[150:153], v[192:195], v[126:129]
	v_mfma_f32_16x16x32_bf16 v[122:125], v[154:157], v[188:191], v[122:125]
	v_mfma_f32_16x16x32_bf16 v[122:125], v[168:171], v[192:195], v[122:125]
	v_mfma_f32_16x16x32_bf16 v[110:113], v[140:143], v[196:199], v[110:113]
	v_mfma_f32_16x16x32_bf16 v[110:113], v[150:153], v[200:203], v[110:113]
	v_mfma_f32_16x16x32_bf16 v[106:109], v[154:157], v[196:199], v[106:109]
	v_mfma_f32_16x16x32_bf16 v[106:109], v[168:171], v[200:203], v[106:109]
	v_mfma_f32_16x16x32_bf16 v[94:97], v[140:143], v[204:207], v[94:97]
	v_mfma_f32_16x16x32_bf16 v[94:97], v[150:153], v[216:219], v[94:97]
	v_mfma_f32_16x16x32_bf16 v[90:93], v[154:157], v[204:207], v[90:93]
	v_mfma_f32_16x16x32_bf16 v[90:93], v[168:171], v[216:219], v[90:93]
	v_mfma_f32_16x16x32_bf16 v[78:81], v[140:143], v[220:223], v[78:81]
	v_mfma_f32_16x16x32_bf16 v[78:81], v[150:153], v[224:227], v[78:81]
	v_mfma_f32_16x16x32_bf16 v[74:77], v[154:157], v[220:223], v[74:77]
	v_mfma_f32_16x16x32_bf16 v[74:77], v[168:171], v[224:227], v[74:77]
	v_mfma_f32_16x16x32_bf16 v[118:121], v[172:175], v[188:191], v[118:121]
	v_mfma_f32_16x16x32_bf16 v[118:121], v[176:179], v[192:195], v[118:121]
	v_mfma_f32_16x16x32_bf16 v[114:117], v[180:183], v[188:191], v[114:117]
	v_mfma_f32_16x16x32_bf16 v[114:117], v[184:187], v[192:195], v[114:117]
	v_mfma_f32_16x16x32_bf16 v[102:105], v[172:175], v[196:199], v[102:105]
	v_mfma_f32_16x16x32_bf16 v[102:105], v[176:179], v[200:203], v[102:105]
	v_mfma_f32_16x16x32_bf16 v[98:101], v[180:183], v[196:199], v[98:101]
	v_mfma_f32_16x16x32_bf16 v[98:101], v[184:187], v[200:203], v[98:101]
	v_mfma_f32_16x16x32_bf16 v[86:89], v[172:175], v[204:207], v[86:89]
	v_mfma_f32_16x16x32_bf16 v[86:89], v[176:179], v[216:219], v[86:89]
	v_mfma_f32_16x16x32_bf16 v[82:85], v[180:183], v[204:207], v[82:85]
	v_mfma_f32_16x16x32_bf16 v[82:85], v[184:187], v[216:219], v[82:85]
	v_mfma_f32_16x16x32_bf16 v[70:73], v[172:175], v[220:223], v[70:73]
	v_mfma_f32_16x16x32_bf16 v[70:73], v[176:179], v[224:227], v[70:73]
	v_mfma_f32_16x16x32_bf16 v[66:69], v[180:183], v[220:223], v[66:69]
	v_mfma_f32_16x16x32_bf16 v[66:69], v[184:187], v[224:227], v[66:69]
	s_barrier
	s_add_i32 s0, s27, s58
	v_lshl_add_u64 v[144:145], v[144:145], 0, s[56:57]
	s_mov_b32 m0, s0
	ds_read_b128 v[188:191], v148 offset:49152
	ds_read_b128 v[192:195], v148 offset:50176
	ds_read_b128 v[196:199], v148 offset:51200
	ds_read_b128 v[200:203], v148 offset:52224
	ds_read_b128 v[204:207], v148 offset:53248
	ds_read_b128 v[216:219], v148 offset:54272
	ds_read_b128 v[220:223], v148 offset:55296
	ds_read_b128 v[224:227], v148 offset:56320
	global_load_lds_dwordx4 v[144:145], off
	s_add_i32 m0, s0, 0x2000
	s_add_u32 s0, s14, 0x158080
	v_lshl_add_u64 v[144:145], v[228:229], 0, s[56:57]
	s_addc_u32 s1, s15, 0
	s_add_i32 s14, s28, s58
	global_load_lds_dwordx4 v[144:145], off
	v_lshl_add_u64 v[144:145], s[0:1], 0, v[158:159]
	s_mov_b32 m0, s14
	s_nop 0
	global_load_lds_dwordx4 v[144:145], off
	v_lshl_add_u64 v[144:145], s[0:1], 0, v[134:135]
	s_add_i32 m0, s14, 0x2000
	s_nop 0
	global_load_lds_dwordx4 v[144:145], off
	v_lshl_add_u64 v[144:145], v[230:231], 0, s[56:57]
	s_mov_b32 m0, s73
	s_nop 0
	global_load_lds_dwordx4 v[144:145], off
	v_lshl_add_u64 v[144:145], v[232:233], 0, s[56:57]
	s_mov_b32 m0, s74
	s_nop 0
	global_load_lds_dwordx4 v[144:145], off
	s_waitcnt vmcnt(8)
	s_waitcnt lgkmcnt(0)
	s_barrier
	s_waitcnt lgkmcnt(0)
	v_mfma_f32_16x16x32_bf16 v[62:65], v[140:143], v[188:191], v[62:65]
	v_mfma_f32_16x16x32_bf16 v[62:65], v[150:153], v[192:195], v[62:65]
	v_mfma_f32_16x16x32_bf16 v[58:61], v[154:157], v[188:191], v[58:61]
	v_mfma_f32_16x16x32_bf16 v[58:61], v[168:171], v[192:195], v[58:61]
	v_mfma_f32_16x16x32_bf16 v[46:49], v[140:143], v[196:199], v[46:49]
	v_mfma_f32_16x16x32_bf16 v[46:49], v[150:153], v[200:203], v[46:49]
	v_mfma_f32_16x16x32_bf16 v[42:45], v[154:157], v[196:199], v[42:45]
	v_mfma_f32_16x16x32_bf16 v[42:45], v[168:171], v[200:203], v[42:45]
	v_mfma_f32_16x16x32_bf16 v[30:33], v[140:143], v[204:207], v[30:33]
	v_mfma_f32_16x16x32_bf16 v[30:33], v[150:153], v[216:219], v[30:33]
	v_mfma_f32_16x16x32_bf16 v[26:29], v[154:157], v[204:207], v[26:29]
	v_mfma_f32_16x16x32_bf16 v[26:29], v[168:171], v[216:219], v[26:29]
	v_mfma_f32_16x16x32_bf16 v[14:17], v[140:143], v[220:223], v[14:17]
	v_mfma_f32_16x16x32_bf16 v[14:17], v[150:153], v[224:227], v[14:17]
	v_mfma_f32_16x16x32_bf16 v[10:13], v[154:157], v[220:223], v[10:13]
	v_mfma_f32_16x16x32_bf16 v[10:13], v[168:171], v[224:227], v[10:13]
	v_mfma_f32_16x16x32_bf16 v[54:57], v[172:175], v[188:191], v[54:57]
	v_mfma_f32_16x16x32_bf16 v[54:57], v[176:179], v[192:195], v[54:57]
	v_mfma_f32_16x16x32_bf16 v[50:53], v[180:183], v[188:191], v[50:53]
	v_mfma_f32_16x16x32_bf16 v[50:53], v[184:187], v[192:195], v[50:53]
	v_mfma_f32_16x16x32_bf16 v[38:41], v[172:175], v[196:199], v[38:41]
	v_mfma_f32_16x16x32_bf16 v[38:41], v[176:179], v[200:203], v[38:41]
	v_mfma_f32_16x16x32_bf16 v[34:37], v[180:183], v[196:199], v[34:37]
	v_mfma_f32_16x16x32_bf16 v[34:37], v[184:187], v[200:203], v[34:37]
	v_mfma_f32_16x16x32_bf16 v[22:25], v[172:175], v[204:207], v[22:25]
	v_mfma_f32_16x16x32_bf16 v[22:25], v[176:179], v[216:219], v[22:25]
	v_mfma_f32_16x16x32_bf16 v[18:21], v[180:183], v[204:207], v[18:21]
	v_mfma_f32_16x16x32_bf16 v[18:21], v[184:187], v[216:219], v[18:21]
	v_mfma_f32_16x16x32_bf16 v[6:9], v[172:175], v[220:223], v[6:9]
	v_mfma_f32_16x16x32_bf16 v[6:9], v[176:179], v[224:227], v[6:9]
	v_mfma_f32_16x16x32_bf16 v[2:5], v[180:183], v[220:223], v[2:5]
	v_mfma_f32_16x16x32_bf16 v[2:5], v[184:187], v[224:227], v[2:5]
	s_barrier
	s_add_i32 s26, s26, 2
	s_add_u32 s24, s24, 0x100
	s_addc_u32 s25, s25, 0
	s_cmpk_gt_u32 s26, 0x53
	s_mov_b64 s[0:1], s[36:37]
	s_cbranch_scc0 .LBB0_353
	s_and_b64 vcc, exec, s[12:13]
	s_cbranch_vccz .LBB0_356
	s_barrier

.Lsp_LBB0715:
	s_add_u32 s14, s66, 0xfff80080
	s_addc_u32 s15, s67, -1
	s_add_i32 s24, 0, 0x10000
	s_cmp_eq_u32 s17, 28
	s_cselect_b32 s69, s49, s15
	s_cselect_b32 s68, s48, s14
	v_add_u32_e32 v147, s24, v144
	s_cselect_b32 s15, s1, s16
	s_cselect_b32 s14, s10, s11
	s_add_i32 s26, 0, 0x14000
	ds_read_b128 v[140:143], v147
	ds_read_b128 v[148:151], v147 offset:1024
	ds_read_b128 v[152:155], v147 offset:2048
	ds_read_b128 v[168:171], v147 offset:3072
	v_add_u32_e32 v147, s26, v144
	ds_read_b128 v[172:175], v147
	ds_read_b128 v[176:179], v147 offset:1024
	ds_read_b128 v[180:183], v147 offset:2048
	ds_read_b128 v[184:187], v147 offset:3072
	v_lshl_add_u64 v[156:157], s[66:67], 0, v[136:137]
	s_add_i32 m0, s65, 0xc000
	ds_read_b128 v[188:191], v146
	ds_read_b128 v[192:195], v146 offset:1024
	ds_read_b128 v[196:199], v146 offset:2048
	ds_read_b128 v[200:203], v146 offset:3072
	ds_read_b128 v[204:207], v146 offset:4096
	ds_read_b128 v[216:219], v146 offset:5120
	ds_read_b128 v[220:223], v146 offset:6144
	ds_read_b128 v[224:227], v146 offset:7168
	global_load_lds_dwordx4 v[156:157], off
	v_lshl_add_u64 v[156:157], s[66:67], 0, v[138:139]
	s_add_i32 m0, s65, 0xe000
	s_nop 0
	global_load_lds_dwordx4 v[156:157], off
	s_waitcnt vmcnt(8)
	s_waitcnt lgkmcnt(0)
	s_barrier
	s_waitcnt lgkmcnt(0)
	v_mfma_f32_16x16x32_bf16 v[126:129], v[140:143], v[188:191], v[126:129]
	v_mfma_f32_16x16x32_bf16 v[126:129], v[148:151], v[192:195], v[126:129]
	v_mfma_f32_16x16x32_bf16 v[118:121], v[152:155], v[188:191], v[118:121]
	v_mfma_f32_16x16x32_bf16 v[118:121], v[168:171], v[192:195], v[118:121]
	v_mfma_f32_16x16x32_bf16 v[106:109], v[140:143], v[196:199], v[106:109]
	v_mfma_f32_16x16x32_bf16 v[106:109], v[148:151], v[200:203], v[106:109]
	v_mfma_f32_16x16x32_bf16 v[98:101], v[152:155], v[196:199], v[98:101]
	v_mfma_f32_16x16x32_bf16 v[98:101], v[168:171], v[200:203], v[98:101]
	v_mfma_f32_16x16x32_bf16 v[90:93], v[140:143], v[204:207], v[90:93]
	v_mfma_f32_16x16x32_bf16 v[90:93], v[148:151], v[216:219], v[90:93]
	v_mfma_f32_16x16x32_bf16 v[82:85], v[152:155], v[204:207], v[82:85]
	v_mfma_f32_16x16x32_bf16 v[82:85], v[168:171], v[216:219], v[82:85]
	v_mfma_f32_16x16x32_bf16 v[74:77], v[140:143], v[220:223], v[74:77]
	v_mfma_f32_16x16x32_bf16 v[74:77], v[148:151], v[224:227], v[74:77]
	v_mfma_f32_16x16x32_bf16 v[66:69], v[152:155], v[220:223], v[66:69]
	v_mfma_f32_16x16x32_bf16 v[66:69], v[168:171], v[224:227], v[66:69]
	v_mfma_f32_16x16x32_bf16 v[122:125], v[172:175], v[188:191], v[122:125]
	v_mfma_f32_16x16x32_bf16 v[122:125], v[176:179], v[192:195], v[122:125]
	v_mfma_f32_16x16x32_bf16 v[114:117], v[180:183], v[188:191], v[114:117]
	v_mfma_f32_16x16x32_bf16 v[114:117], v[184:187], v[192:195], v[114:117]
	v_mfma_f32_16x16x32_bf16 v[110:113], v[172:175], v[196:199], v[110:113]
	v_mfma_f32_16x16x32_bf16 v[110:113], v[176:179], v[200:203], v[110:113]
	v_mfma_f32_16x16x32_bf16 v[102:105], v[180:183], v[196:199], v[102:105]
	v_mfma_f32_16x16x32_bf16 v[102:105], v[184:187], v[200:203], v[102:105]
	v_mfma_f32_16x16x32_bf16 v[94:97], v[172:175], v[204:207], v[94:97]
	v_mfma_f32_16x16x32_bf16 v[94:97], v[176:179], v[216:219], v[94:97]
	v_mfma_f32_16x16x32_bf16 v[86:89], v[180:183], v[204:207], v[86:89]
	v_mfma_f32_16x16x32_bf16 v[86:89], v[184:187], v[216:219], v[86:89]
	v_mfma_f32_16x16x32_bf16 v[78:81], v[172:175], v[220:223], v[78:81]
	v_mfma_f32_16x16x32_bf16 v[78:81], v[176:179], v[224:227], v[78:81]
	v_mfma_f32_16x16x32_bf16 v[70:73], v[180:183], v[220:223], v[70:73]
	v_mfma_f32_16x16x32_bf16 v[70:73], v[184:187], v[224:227], v[70:73]
	s_barrier
	s_add_i32 s24, s24, s59
	v_lshl_add_u64 v[156:157], s[14:15], 0, v[158:159]
	s_mov_b32 m0, s24
	ds_read_b128 v[188:191], v146 offset:16384
	ds_read_b128 v[192:195], v146 offset:17408
	ds_read_b128 v[196:199], v146 offset:18432
	ds_read_b128 v[200:203], v146 offset:19456
	ds_read_b128 v[204:207], v146 offset:20480
	ds_read_b128 v[216:219], v146 offset:21504
	ds_read_b128 v[220:223], v146 offset:22528
	ds_read_b128 v[224:227], v146 offset:23552
	global_load_lds_dwordx4 v[156:157], off
	s_add_i32 m0, s24, 0x2000
	s_add_u32 s24, s14, 0x80000
	v_lshl_add_u64 v[228:229], s[14:15], 0, v[134:135]
	s_addc_u32 s25, s15, 0
	s_add_i32 s26, s26, s59
	global_load_lds_dwordx4 v[228:229], off
	v_lshl_add_u64 v[230:231], s[24:25], 0, v[158:159]
	s_mov_b32 m0, s26
	v_lshl_add_u64 v[232:233], s[68:69], 0, v[132:133]
	global_load_lds_dwordx4 v[230:231], off
	v_lshl_add_u64 v[230:231], s[24:25], 0, v[134:135]
	s_add_i32 m0, s26, 0x2000
	s_nop 0
	global_load_lds_dwordx4 v[230:231], off
	v_lshl_add_u64 v[230:231], s[68:69], 0, v[130:131]
	s_mov_b32 m0, s65
	s_nop 0
	global_load_lds_dwordx4 v[230:231], off
	s_mov_b32 m0, s70
	s_nop 0
	global_load_lds_dwordx4 v[232:233], off
	s_waitcnt vmcnt(8)
	s_waitcnt lgkmcnt(0)
	s_barrier
	s_waitcnt lgkmcnt(0)
	v_mfma_f32_16x16x32_bf16 v[58:61], v[140:143], v[188:191], v[58:61]
	v_mfma_f32_16x16x32_bf16 v[58:61], v[148:151], v[192:195], v[58:61]
	v_mfma_f32_16x16x32_bf16 v[50:53], v[152:155], v[188:191], v[50:53]
	v_mfma_f32_16x16x32_bf16 v[50:53], v[168:171], v[192:195], v[50:53]
	v_mfma_f32_16x16x32_bf16 v[42:45], v[140:143], v[196:199], v[42:45]
	v_mfma_f32_16x16x32_bf16 v[42:45], v[148:151], v[200:203], v[42:45]
	v_mfma_f32_16x16x32_bf16 v[34:37], v[152:155], v[196:199], v[34:37]
	v_mfma_f32_16x16x32_bf16 v[34:37], v[168:171], v[200:203], v[34:37]
	v_mfma_f32_16x16x32_bf16 v[26:29], v[140:143], v[204:207], v[26:29]
	v_mfma_f32_16x16x32_bf16 v[26:29], v[148:151], v[216:219], v[26:29]
	v_mfma_f32_16x16x32_bf16 v[18:21], v[152:155], v[204:207], v[18:21]
	v_mfma_f32_16x16x32_bf16 v[18:21], v[168:171], v[216:219], v[18:21]
	v_mfma_f32_16x16x32_bf16 v[10:13], v[140:143], v[220:223], v[10:13]
	v_mfma_f32_16x16x32_bf16 v[10:13], v[148:151], v[224:227], v[10:13]
	v_mfma_f32_16x16x32_bf16 v[2:5], v[152:155], v[220:223], v[2:5]
	v_mfma_f32_16x16x32_bf16 v[2:5], v[168:171], v[224:227], v[2:5]
	v_mfma_f32_16x16x32_bf16 v[62:65], v[172:175], v[188:191], v[62:65]
	v_mfma_f32_16x16x32_bf16 v[62:65], v[176:179], v[192:195], v[62:65]
	v_mfma_f32_16x16x32_bf16 v[54:57], v[180:183], v[188:191], v[54:57]
	v_mfma_f32_16x16x32_bf16 v[54:57], v[184:187], v[192:195], v[54:57]
	v_mfma_f32_16x16x32_bf16 v[46:49], v[172:175], v[196:199], v[46:49]
	v_mfma_f32_16x16x32_bf16 v[46:49], v[176:179], v[200:203], v[46:49]
	v_mfma_f32_16x16x32_bf16 v[38:41], v[180:183], v[196:199], v[38:41]
	v_mfma_f32_16x16x32_bf16 v[38:41], v[184:187], v[200:203], v[38:41]
	v_mfma_f32_16x16x32_bf16 v[30:33], v[172:175], v[204:207], v[30:33]
	v_mfma_f32_16x16x32_bf16 v[30:33], v[176:179], v[216:219], v[30:33]
	v_mfma_f32_16x16x32_bf16 v[22:25], v[180:183], v[204:207], v[22:25]
	v_mfma_f32_16x16x32_bf16 v[22:25], v[184:187], v[216:219], v[22:25]
	v_mfma_f32_16x16x32_bf16 v[14:17], v[172:175], v[220:223], v[14:17]
	v_mfma_f32_16x16x32_bf16 v[14:17], v[176:179], v[224:227], v[14:17]
	v_mfma_f32_16x16x32_bf16 v[6:9], v[180:183], v[220:223], v[6:9]
	v_mfma_f32_16x16x32_bf16 v[6:9], v[184:187], v[224:227], v[6:9]
	s_barrier
	s_add_i32 s26, 0, 0x18000
	v_add_u32_e32 v147, s26, v144
	s_add_i32 s27, 0, 0x1c000
	ds_read_b128 v[140:143], v147
	ds_read_b128 v[148:151], v147 offset:1024
	ds_read_b128 v[152:155], v147 offset:2048
	ds_read_b128 v[168:171], v147 offset:3072
	v_add_u32_e32 v147, s27, v144
	ds_read_b128 v[172:175], v147
	ds_read_b128 v[176:179], v147 offset:1024
	ds_read_b128 v[180:183], v147 offset:2048
	ds_read_b128 v[184:187], v147 offset:3072
	s_add_u32 s24, s68, 0x80000
	s_addc_u32 s25, s69, 0
	s_mov_b32 m0, s71
	v_lshl_add_u64 v[234:235], s[24:25], 0, v[130:131]
	ds_read_b128 v[188:191], v146 offset:32768
	ds_read_b128 v[192:195], v146 offset:33792
	ds_read_b128 v[196:199], v146 offset:34816
	ds_read_b128 v[200:203], v146 offset:35840
	ds_read_b128 v[204:207], v146 offset:36864
	ds_read_b128 v[216:219], v146 offset:37888
	ds_read_b128 v[220:223], v146 offset:38912
	ds_read_b128 v[224:227], v146 offset:39936
	global_load_lds_dwordx4 v[234:235], off
	v_lshl_add_u64 v[234:235], s[24:25], 0, v[132:133]
	s_mov_b32 m0, s72
	s_nop 0
	global_load_lds_dwordx4 v[234:235], off
	s_waitcnt vmcnt(8)
	s_waitcnt lgkmcnt(0)
	s_barrier
	s_waitcnt lgkmcnt(0)
	v_mfma_f32_16x16x32_bf16 v[126:129], v[140:143], v[188:191], v[126:129]
	v_mfma_f32_16x16x32_bf16 v[126:129], v[148:151], v[192:195], v[126:129]
	v_mfma_f32_16x16x32_bf16 v[118:121], v[152:155], v[188:191], v[118:121]
	v_mfma_f32_16x16x32_bf16 v[118:121], v[168:171], v[192:195], v[118:121]
	v_mfma_f32_16x16x32_bf16 v[106:109], v[140:143], v[196:199], v[106:109]
	v_mfma_f32_16x16x32_bf16 v[106:109], v[148:151], v[200:203], v[106:109]
	v_mfma_f32_16x16x32_bf16 v[98:101], v[152:155], v[196:199], v[98:101]
	v_mfma_f32_16x16x32_bf16 v[98:101], v[168:171], v[200:203], v[98:101]
	v_mfma_f32_16x16x32_bf16 v[90:93], v[140:143], v[204:207], v[90:93]
	v_mfma_f32_16x16x32_bf16 v[90:93], v[148:151], v[216:219], v[90:93]
	v_mfma_f32_16x16x32_bf16 v[82:85], v[152:155], v[204:207], v[82:85]
	v_mfma_f32_16x16x32_bf16 v[82:85], v[168:171], v[216:219], v[82:85]
	v_mfma_f32_16x16x32_bf16 v[74:77], v[140:143], v[220:223], v[74:77]
	v_mfma_f32_16x16x32_bf16 v[74:77], v[148:151], v[224:227], v[74:77]
	v_mfma_f32_16x16x32_bf16 v[66:69], v[152:155], v[220:223], v[66:69]
	v_mfma_f32_16x16x32_bf16 v[66:69], v[168:171], v[224:227], v[66:69]
	v_mfma_f32_16x16x32_bf16 v[122:125], v[172:175], v[188:191], v[122:125]
	v_mfma_f32_16x16x32_bf16 v[122:125], v[176:179], v[192:195], v[122:125]
	v_mfma_f32_16x16x32_bf16 v[114:117], v[180:183], v[188:191], v[114:117]
	v_mfma_f32_16x16x32_bf16 v[114:117], v[184:187], v[192:195], v[114:117]
	v_mfma_f32_16x16x32_bf16 v[110:113], v[172:175], v[196:199], v[110:113]
	v_mfma_f32_16x16x32_bf16 v[110:113], v[176:179], v[200:203], v[110:113]
	v_mfma_f32_16x16x32_bf16 v[102:105], v[180:183], v[196:199], v[102:105]
	v_mfma_f32_16x16x32_bf16 v[102:105], v[184:187], v[200:203], v[102:105]
	v_mfma_f32_16x16x32_bf16 v[94:97], v[172:175], v[204:207], v[94:97]
	v_mfma_f32_16x16x32_bf16 v[94:97], v[176:179], v[216:219], v[94:97]
	v_mfma_f32_16x16x32_bf16 v[86:89], v[180:183], v[204:207], v[86:89]
	v_mfma_f32_16x16x32_bf16 v[86:89], v[184:187], v[216:219], v[86:89]
	v_mfma_f32_16x16x32_bf16 v[78:81], v[172:175], v[220:223], v[78:81]
	v_mfma_f32_16x16x32_bf16 v[78:81], v[176:179], v[224:227], v[78:81]
	v_mfma_f32_16x16x32_bf16 v[70:73], v[180:183], v[220:223], v[70:73]
	v_mfma_f32_16x16x32_bf16 v[70:73], v[184:187], v[224:227], v[70:73]
	s_barrier
	s_add_i32 s24, s26, s59
	v_lshl_add_u64 v[156:157], v[156:157], 0, s[56:57]
	s_mov_b32 m0, s24
	ds_read_b128 v[188:191], v146 offset:49152
	ds_read_b128 v[192:195], v146 offset:50176
	ds_read_b128 v[196:199], v146 offset:51200
	ds_read_b128 v[200:203], v146 offset:52224
	ds_read_b128 v[204:207], v146 offset:53248
	ds_read_b128 v[216:219], v146 offset:54272
	ds_read_b128 v[220:223], v146 offset:55296
	ds_read_b128 v[224:227], v146 offset:56320
	global_load_lds_dwordx4 v[156:157], off
	s_add_i32 m0, s24, 0x2000
	s_add_u32 s14, s14, 0x80080
	v_lshl_add_u64 v[156:157], v[228:229], 0, s[56:57]
	s_addc_u32 s15, s15, 0
	s_add_i32 s24, s27, s59
	global_load_lds_dwordx4 v[156:157], off
	v_lshl_add_u64 v[156:157], s[14:15], 0, v[158:159]
	s_mov_b32 m0, s24
	s_nop 0
	global_load_lds_dwordx4 v[156:157], off
	v_lshl_add_u64 v[156:157], s[14:15], 0, v[134:135]
	s_add_i32 m0, s24, 0x2000
	s_nop 0
	global_load_lds_dwordx4 v[156:157], off
	v_lshl_add_u64 v[156:157], v[230:231], 0, s[56:57]
	s_mov_b32 m0, s54
	s_nop 0
	global_load_lds_dwordx4 v[156:157], off
	v_lshl_add_u64 v[156:157], v[232:233], 0, s[56:57]
	s_mov_b32 m0, s73
	s_nop 0
	global_load_lds_dwordx4 v[156:157], off
	s_waitcnt vmcnt(8)
	s_waitcnt lgkmcnt(0)
	s_barrier
	s_waitcnt lgkmcnt(0)
	v_mfma_f32_16x16x32_bf16 v[58:61], v[140:143], v[188:191], v[58:61]
	v_mfma_f32_16x16x32_bf16 v[58:61], v[148:151], v[192:195], v[58:61]
	v_mfma_f32_16x16x32_bf16 v[50:53], v[152:155], v[188:191], v[50:53]
	v_mfma_f32_16x16x32_bf16 v[50:53], v[168:171], v[192:195], v[50:53]
	v_mfma_f32_16x16x32_bf16 v[42:45], v[140:143], v[196:199], v[42:45]
	v_mfma_f32_16x16x32_bf16 v[42:45], v[148:151], v[200:203], v[42:45]
	v_mfma_f32_16x16x32_bf16 v[34:37], v[152:155], v[196:199], v[34:37]
	v_mfma_f32_16x16x32_bf16 v[34:37], v[168:171], v[200:203], v[34:37]
	v_mfma_f32_16x16x32_bf16 v[26:29], v[140:143], v[204:207], v[26:29]
	v_mfma_f32_16x16x32_bf16 v[26:29], v[148:151], v[216:219], v[26:29]
	v_mfma_f32_16x16x32_bf16 v[18:21], v[152:155], v[204:207], v[18:21]
	v_mfma_f32_16x16x32_bf16 v[18:21], v[168:171], v[216:219], v[18:21]
	v_mfma_f32_16x16x32_bf16 v[10:13], v[140:143], v[220:223], v[10:13]
	v_mfma_f32_16x16x32_bf16 v[10:13], v[148:151], v[224:227], v[10:13]
	v_mfma_f32_16x16x32_bf16 v[2:5], v[152:155], v[220:223], v[2:5]
	v_mfma_f32_16x16x32_bf16 v[2:5], v[168:171], v[224:227], v[2:5]
	v_mfma_f32_16x16x32_bf16 v[62:65], v[172:175], v[188:191], v[62:65]
	v_mfma_f32_16x16x32_bf16 v[62:65], v[176:179], v[192:195], v[62:65]
	v_mfma_f32_16x16x32_bf16 v[54:57], v[180:183], v[188:191], v[54:57]
	v_mfma_f32_16x16x32_bf16 v[54:57], v[184:187], v[192:195], v[54:57]
	v_mfma_f32_16x16x32_bf16 v[46:49], v[172:175], v[196:199], v[46:49]
	v_mfma_f32_16x16x32_bf16 v[46:49], v[176:179], v[200:203], v[46:49]
	v_mfma_f32_16x16x32_bf16 v[38:41], v[180:183], v[196:199], v[38:41]
	v_mfma_f32_16x16x32_bf16 v[38:41], v[184:187], v[200:203], v[38:41]
	v_mfma_f32_16x16x32_bf16 v[30:33], v[172:175], v[204:207], v[30:33]
	v_mfma_f32_16x16x32_bf16 v[30:33], v[176:179], v[216:219], v[30:33]
	v_mfma_f32_16x16x32_bf16 v[22:25], v[180:183], v[204:207], v[22:25]
	v_mfma_f32_16x16x32_bf16 v[22:25], v[184:187], v[216:219], v[22:25]
	v_mfma_f32_16x16x32_bf16 v[14:17], v[172:175], v[220:223], v[14:17]
	v_mfma_f32_16x16x32_bf16 v[14:17], v[176:179], v[224:227], v[14:17]
	v_mfma_f32_16x16x32_bf16 v[6:9], v[180:183], v[220:223], v[6:9]
	v_mfma_f32_16x16x32_bf16 v[6:9], v[184:187], v[224:227], v[6:9]
	s_barrier
	s_add_i32 s17, s17, 2
	s_add_u32 s66, s66, 0x100
	s_addc_u32 s67, s67, 0
	s_add_u32 s11, s11, 0x100
	s_addc_u32 s16, s16, 0
	s_cmp_gt_u32 s17, 29
	s_cbranch_scc0 .LBB0_715
	s_and_b64 vcc, exec, s[22:23]
	s_cbranch_vccz .LBB0_718
	s_barrier

.Lsp_LBB0801:
	s_add_u32 s14, s50, 0xfff80080
	s_addc_u32 s15, s51, -1
	s_add_i32 s30, 0, 0x10000
	s_cmp_eq_u32 s29, 28
	s_cselect_b32 s65, s43, s15
	s_cselect_b32 s64, s42, s14
	v_add_u32_e32 v150, s30, v152
	s_cselect_b32 s15, s1, s23
	s_cselect_b32 s14, s16, s17
	s_add_i32 s34, 0, 0x14000
	ds_read_b128 v[142:145], v150
	ds_read_b128 v[146:149], v150 offset:1024
	ds_read_b128 v[168:171], v150 offset:2048
	ds_read_b128 v[172:175], v150 offset:3072
	v_add_u32_e32 v150, s34, v152
	ds_read_b128 v[176:179], v150
	ds_read_b128 v[180:183], v150 offset:1024
	ds_read_b128 v[184:187], v150 offset:2048
	ds_read_b128 v[188:191], v150 offset:3072
	v_lshl_add_u64 v[150:151], s[50:51], 0, v[138:139]
	s_add_i32 m0, s58, 0xc000
	ds_read_b128 v[192:195], v155
	ds_read_b128 v[196:199], v155 offset:1024
	ds_read_b128 v[200:203], v155 offset:2048
	ds_read_b128 v[204:207], v155 offset:3072
	ds_read_b128 v[216:219], v155 offset:4096
	ds_read_b128 v[220:223], v155 offset:5120
	ds_read_b128 v[224:227], v155 offset:6144
	ds_read_b128 v[228:231], v155 offset:7168
	global_load_lds_dwordx4 v[150:151], off
	v_lshl_add_u64 v[150:151], s[50:51], 0, v[140:141]
	s_add_i32 m0, s58, 0xe000
	s_nop 0
	global_load_lds_dwordx4 v[150:151], off
	s_waitcnt vmcnt(8)
	s_waitcnt lgkmcnt(0)
	s_barrier
	s_waitcnt lgkmcnt(0)
	v_mfma_f32_16x16x32_bf16 v[126:129], v[142:145], v[192:195], v[126:129]
	v_mfma_f32_16x16x32_bf16 v[126:129], v[146:149], v[196:199], v[126:129]
	v_mfma_f32_16x16x32_bf16 v[122:125], v[168:171], v[192:195], v[122:125]
	v_mfma_f32_16x16x32_bf16 v[122:125], v[172:175], v[196:199], v[122:125]
	v_mfma_f32_16x16x32_bf16 v[110:113], v[142:145], v[200:203], v[110:113]
	v_mfma_f32_16x16x32_bf16 v[110:113], v[146:149], v[204:207], v[110:113]
	v_mfma_f32_16x16x32_bf16 v[106:109], v[168:171], v[200:203], v[106:109]
	v_mfma_f32_16x16x32_bf16 v[106:109], v[172:175], v[204:207], v[106:109]
	v_mfma_f32_16x16x32_bf16 v[94:97], v[142:145], v[216:219], v[94:97]
	v_mfma_f32_16x16x32_bf16 v[94:97], v[146:149], v[220:223], v[94:97]
	v_mfma_f32_16x16x32_bf16 v[90:93], v[168:171], v[216:219], v[90:93]
	v_mfma_f32_16x16x32_bf16 v[90:93], v[172:175], v[220:223], v[90:93]
	v_mfma_f32_16x16x32_bf16 v[78:81], v[142:145], v[224:227], v[78:81]
	v_mfma_f32_16x16x32_bf16 v[78:81], v[146:149], v[228:231], v[78:81]
	v_mfma_f32_16x16x32_bf16 v[74:77], v[168:171], v[224:227], v[74:77]
	v_mfma_f32_16x16x32_bf16 v[74:77], v[172:175], v[228:231], v[74:77]
	v_mfma_f32_16x16x32_bf16 v[118:121], v[176:179], v[192:195], v[118:121]
	v_mfma_f32_16x16x32_bf16 v[118:121], v[180:183], v[196:199], v[118:121]
	v_mfma_f32_16x16x32_bf16 v[114:117], v[184:187], v[192:195], v[114:117]
	v_mfma_f32_16x16x32_bf16 v[114:117], v[188:191], v[196:199], v[114:117]
	v_mfma_f32_16x16x32_bf16 v[102:105], v[176:179], v[200:203], v[102:105]
	v_mfma_f32_16x16x32_bf16 v[102:105], v[180:183], v[204:207], v[102:105]
	v_mfma_f32_16x16x32_bf16 v[98:101], v[184:187], v[200:203], v[98:101]
	v_mfma_f32_16x16x32_bf16 v[98:101], v[188:191], v[204:207], v[98:101]
	v_mfma_f32_16x16x32_bf16 v[86:89], v[176:179], v[216:219], v[86:89]
	v_mfma_f32_16x16x32_bf16 v[86:89], v[180:183], v[220:223], v[86:89]
	v_mfma_f32_16x16x32_bf16 v[82:85], v[184:187], v[216:219], v[82:85]
	v_mfma_f32_16x16x32_bf16 v[82:85], v[188:191], v[220:223], v[82:85]
	v_mfma_f32_16x16x32_bf16 v[70:73], v[176:179], v[224:227], v[70:73]
	v_mfma_f32_16x16x32_bf16 v[70:73], v[180:183], v[228:231], v[70:73]
	v_mfma_f32_16x16x32_bf16 v[66:69], v[184:187], v[224:227], v[66:69]
	v_mfma_f32_16x16x32_bf16 v[66:69], v[188:191], v[228:231], v[66:69]
	s_barrier
	s_add_i32 s30, s30, s11
	v_lshl_add_u64 v[150:151], s[14:15], 0, v[158:159]
	s_mov_b32 m0, s30
	ds_read_b128 v[192:195], v155 offset:16384
	ds_read_b128 v[196:199], v155 offset:17408
	ds_read_b128 v[200:203], v155 offset:18432
	ds_read_b128 v[204:207], v155 offset:19456
	ds_read_b128 v[216:219], v155 offset:20480
	ds_read_b128 v[220:223], v155 offset:21504
	ds_read_b128 v[224:227], v155 offset:22528
	ds_read_b128 v[228:231], v155 offset:23552
	global_load_lds_dwordx4 v[150:151], off
	s_add_i32 m0, s30, 0x2000
	s_add_u32 s30, s14, 0x80000
	v_lshl_add_u64 v[156:157], s[14:15], 0, v[134:135]
	s_addc_u32 s31, s15, 0
	s_add_i32 s34, s34, s11
	global_load_lds_dwordx4 v[156:157], off
	v_lshl_add_u64 v[232:233], s[30:31], 0, v[158:159]
	s_mov_b32 m0, s34
	v_lshl_add_u64 v[234:235], s[64:65], 0, v[132:133]
	global_load_lds_dwordx4 v[232:233], off
	v_lshl_add_u64 v[232:233], s[30:31], 0, v[134:135]
	s_add_i32 m0, s34, 0x2000
	s_nop 0
	global_load_lds_dwordx4 v[232:233], off
	v_lshl_add_u64 v[232:233], s[64:65], 0, v[130:131]
	s_mov_b32 m0, s58
	s_nop 0
	global_load_lds_dwordx4 v[232:233], off
	s_mov_b32 m0, s24
	s_nop 0
	global_load_lds_dwordx4 v[234:235], off
	s_waitcnt vmcnt(8)
	s_waitcnt lgkmcnt(0)
	s_barrier
	s_waitcnt lgkmcnt(0)
	v_mfma_f32_16x16x32_bf16 v[62:65], v[142:145], v[192:195], v[62:65]
	v_mfma_f32_16x16x32_bf16 v[62:65], v[146:149], v[196:199], v[62:65]
	v_mfma_f32_16x16x32_bf16 v[58:61], v[168:171], v[192:195], v[58:61]
	v_mfma_f32_16x16x32_bf16 v[58:61], v[172:175], v[196:199], v[58:61]
	v_mfma_f32_16x16x32_bf16 v[46:49], v[142:145], v[200:203], v[46:49]
	v_mfma_f32_16x16x32_bf16 v[46:49], v[146:149], v[204:207], v[46:49]
	v_mfma_f32_16x16x32_bf16 v[42:45], v[168:171], v[200:203], v[42:45]
	v_mfma_f32_16x16x32_bf16 v[42:45], v[172:175], v[204:207], v[42:45]
	v_mfma_f32_16x16x32_bf16 v[30:33], v[142:145], v[216:219], v[30:33]
	v_mfma_f32_16x16x32_bf16 v[30:33], v[146:149], v[220:223], v[30:33]
	v_mfma_f32_16x16x32_bf16 v[26:29], v[168:171], v[216:219], v[26:29]
	v_mfma_f32_16x16x32_bf16 v[26:29], v[172:175], v[220:223], v[26:29]
	v_mfma_f32_16x16x32_bf16 v[14:17], v[142:145], v[224:227], v[14:17]
	v_mfma_f32_16x16x32_bf16 v[14:17], v[146:149], v[228:231], v[14:17]
	v_mfma_f32_16x16x32_bf16 v[10:13], v[168:171], v[224:227], v[10:13]
	v_mfma_f32_16x16x32_bf16 v[10:13], v[172:175], v[228:231], v[10:13]
	v_mfma_f32_16x16x32_bf16 v[54:57], v[176:179], v[192:195], v[54:57]
	v_mfma_f32_16x16x32_bf16 v[54:57], v[180:183], v[196:199], v[54:57]
	v_mfma_f32_16x16x32_bf16 v[50:53], v[184:187], v[192:195], v[50:53]
	v_mfma_f32_16x16x32_bf16 v[50:53], v[188:191], v[196:199], v[50:53]
	v_mfma_f32_16x16x32_bf16 v[38:41], v[176:179], v[200:203], v[38:41]
	v_mfma_f32_16x16x32_bf16 v[38:41], v[180:183], v[204:207], v[38:41]
	v_mfma_f32_16x16x32_bf16 v[34:37], v[184:187], v[200:203], v[34:37]
	v_mfma_f32_16x16x32_bf16 v[34:37], v[188:191], v[204:207], v[34:37]
	v_mfma_f32_16x16x32_bf16 v[22:25], v[176:179], v[216:219], v[22:25]
	v_mfma_f32_16x16x32_bf16 v[22:25], v[180:183], v[220:223], v[22:25]
	v_mfma_f32_16x16x32_bf16 v[18:21], v[184:187], v[216:219], v[18:21]
	v_mfma_f32_16x16x32_bf16 v[18:21], v[188:191], v[220:223], v[18:21]
	v_mfma_f32_16x16x32_bf16 v[6:9], v[176:179], v[224:227], v[6:9]
	v_mfma_f32_16x16x32_bf16 v[6:9], v[180:183], v[228:231], v[6:9]
	v_mfma_f32_16x16x32_bf16 v[2:5], v[184:187], v[224:227], v[2:5]
	v_mfma_f32_16x16x32_bf16 v[2:5], v[188:191], v[228:231], v[2:5]
	s_barrier
	s_add_i32 s34, 0, 0x18000
	v_add_u32_e32 v161, s34, v152
	s_add_i32 s35, 0, 0x1c000
	ds_read_b128 v[142:145], v161
	ds_read_b128 v[146:149], v161 offset:1024
	ds_read_b128 v[168:171], v161 offset:2048
	ds_read_b128 v[172:175], v161 offset:3072
	v_add_u32_e32 v161, s35, v152
	ds_read_b128 v[176:179], v161
	ds_read_b128 v[180:183], v161 offset:1024
	ds_read_b128 v[184:187], v161 offset:2048
	ds_read_b128 v[188:191], v161 offset:3072
	s_add_u32 s30, s64, 0x80000
	s_addc_u32 s31, s65, 0
	s_mov_b32 m0, s25
	v_lshl_add_u64 v[236:237], s[30:31], 0, v[130:131]
	ds_read_b128 v[192:195], v155 offset:32768
	ds_read_b128 v[196:199], v155 offset:33792
	ds_read_b128 v[200:203], v155 offset:34816
	ds_read_b128 v[204:207], v155 offset:35840
	ds_read_b128 v[216:219], v155 offset:36864
	ds_read_b128 v[220:223], v155 offset:37888
	ds_read_b128 v[224:227], v155 offset:38912
	ds_read_b128 v[228:231], v155 offset:39936
	global_load_lds_dwordx4 v[236:237], off
	v_lshl_add_u64 v[236:237], s[30:31], 0, v[132:133]
	s_mov_b32 m0, s59
	s_nop 0
	global_load_lds_dwordx4 v[236:237], off
	s_waitcnt vmcnt(8)
	s_waitcnt lgkmcnt(0)
	s_barrier
	s_waitcnt lgkmcnt(0)
	v_mfma_f32_16x16x32_bf16 v[126:129], v[142:145], v[192:195], v[126:129]
	v_mfma_f32_16x16x32_bf16 v[126:129], v[146:149], v[196:199], v[126:129]
	v_mfma_f32_16x16x32_bf16 v[122:125], v[168:171], v[192:195], v[122:125]
	v_mfma_f32_16x16x32_bf16 v[122:125], v[172:175], v[196:199], v[122:125]
	v_mfma_f32_16x16x32_bf16 v[110:113], v[142:145], v[200:203], v[110:113]
	v_mfma_f32_16x16x32_bf16 v[110:113], v[146:149], v[204:207], v[110:113]
	v_mfma_f32_16x16x32_bf16 v[106:109], v[168:171], v[200:203], v[106:109]
	v_mfma_f32_16x16x32_bf16 v[106:109], v[172:175], v[204:207], v[106:109]
	v_mfma_f32_16x16x32_bf16 v[94:97], v[142:145], v[216:219], v[94:97]
	v_mfma_f32_16x16x32_bf16 v[94:97], v[146:149], v[220:223], v[94:97]
	v_mfma_f32_16x16x32_bf16 v[90:93], v[168:171], v[216:219], v[90:93]
	v_mfma_f32_16x16x32_bf16 v[90:93], v[172:175], v[220:223], v[90:93]
	v_mfma_f32_16x16x32_bf16 v[78:81], v[142:145], v[224:227], v[78:81]
	v_mfma_f32_16x16x32_bf16 v[78:81], v[146:149], v[228:231], v[78:81]
	v_mfma_f32_16x16x32_bf16 v[74:77], v[168:171], v[224:227], v[74:77]
	v_mfma_f32_16x16x32_bf16 v[74:77], v[172:175], v[228:231], v[74:77]
	v_mfma_f32_16x16x32_bf16 v[118:121], v[176:179], v[192:195], v[118:121]
	v_mfma_f32_16x16x32_bf16 v[118:121], v[180:183], v[196:199], v[118:121]
	v_mfma_f32_16x16x32_bf16 v[114:117], v[184:187], v[192:195], v[114:117]
	v_mfma_f32_16x16x32_bf16 v[114:117], v[188:191], v[196:199], v[114:117]
	v_mfma_f32_16x16x32_bf16 v[102:105], v[176:179], v[200:203], v[102:105]
	v_mfma_f32_16x16x32_bf16 v[102:105], v[180:183], v[204:207], v[102:105]
	v_mfma_f32_16x16x32_bf16 v[98:101], v[184:187], v[200:203], v[98:101]
	v_mfma_f32_16x16x32_bf16 v[98:101], v[188:191], v[204:207], v[98:101]
	v_mfma_f32_16x16x32_bf16 v[86:89], v[176:179], v[216:219], v[86:89]
	v_mfma_f32_16x16x32_bf16 v[86:89], v[180:183], v[220:223], v[86:89]
	v_mfma_f32_16x16x32_bf16 v[82:85], v[184:187], v[216:219], v[82:85]
	v_mfma_f32_16x16x32_bf16 v[82:85], v[188:191], v[220:223], v[82:85]
	v_mfma_f32_16x16x32_bf16 v[70:73], v[176:179], v[224:227], v[70:73]
	v_mfma_f32_16x16x32_bf16 v[70:73], v[180:183], v[228:231], v[70:73]
	v_mfma_f32_16x16x32_bf16 v[66:69], v[184:187], v[224:227], v[66:69]
	v_mfma_f32_16x16x32_bf16 v[66:69], v[188:191], v[228:231], v[66:69]
	s_barrier
	s_add_i32 s30, s34, s11
	v_lshl_add_u64 v[150:151], v[150:151], 0, s[56:57]
	s_mov_b32 m0, s30
	ds_read_b128 v[192:195], v155 offset:49152
	ds_read_b128 v[196:199], v155 offset:50176
	ds_read_b128 v[200:203], v155 offset:51200
	ds_read_b128 v[204:207], v155 offset:52224
	ds_read_b128 v[216:219], v155 offset:53248
	ds_read_b128 v[220:223], v155 offset:54272
	ds_read_b128 v[224:227], v155 offset:55296
	ds_read_b128 v[228:231], v155 offset:56320
	global_load_lds_dwordx4 v[150:151], off
	s_add_i32 m0, s30, 0x2000
	s_add_u32 s14, s14, 0x80080
	v_lshl_add_u64 v[150:151], v[156:157], 0, s[56:57]
	s_addc_u32 s15, s15, 0
	s_add_i32 s30, s35, s11
	global_load_lds_dwordx4 v[150:151], off
	v_lshl_add_u64 v[150:151], s[14:15], 0, v[158:159]
	s_mov_b32 m0, s30
	s_nop 0
	global_load_lds_dwordx4 v[150:151], off
	v_lshl_add_u64 v[150:151], s[14:15], 0, v[134:135]
	s_add_i32 m0, s30, 0x2000
	s_nop 0
	global_load_lds_dwordx4 v[150:151], off
	v_lshl_add_u64 v[150:151], v[232:233], 0, s[56:57]
	s_mov_b32 m0, s26
	s_nop 0
	global_load_lds_dwordx4 v[150:151], off
	v_lshl_add_u64 v[150:151], v[234:235], 0, s[56:57]
	s_mov_b32 m0, s27
	s_nop 0
	global_load_lds_dwordx4 v[150:151], off
	s_waitcnt vmcnt(8)
	s_waitcnt lgkmcnt(0)
	s_barrier
	s_waitcnt lgkmcnt(0)
	v_mfma_f32_16x16x32_bf16 v[62:65], v[142:145], v[192:195], v[62:65]
	v_mfma_f32_16x16x32_bf16 v[62:65], v[146:149], v[196:199], v[62:65]
	v_mfma_f32_16x16x32_bf16 v[58:61], v[168:171], v[192:195], v[58:61]
	v_mfma_f32_16x16x32_bf16 v[58:61], v[172:175], v[196:199], v[58:61]
	v_mfma_f32_16x16x32_bf16 v[46:49], v[142:145], v[200:203], v[46:49]
	v_mfma_f32_16x16x32_bf16 v[46:49], v[146:149], v[204:207], v[46:49]
	v_mfma_f32_16x16x32_bf16 v[42:45], v[168:171], v[200:203], v[42:45]
	v_mfma_f32_16x16x32_bf16 v[42:45], v[172:175], v[204:207], v[42:45]
	v_mfma_f32_16x16x32_bf16 v[30:33], v[142:145], v[216:219], v[30:33]
	v_mfma_f32_16x16x32_bf16 v[30:33], v[146:149], v[220:223], v[30:33]
	v_mfma_f32_16x16x32_bf16 v[26:29], v[168:171], v[216:219], v[26:29]
	v_mfma_f32_16x16x32_bf16 v[26:29], v[172:175], v[220:223], v[26:29]
	v_mfma_f32_16x16x32_bf16 v[14:17], v[142:145], v[224:227], v[14:17]
	v_mfma_f32_16x16x32_bf16 v[14:17], v[146:149], v[228:231], v[14:17]
	v_mfma_f32_16x16x32_bf16 v[10:13], v[168:171], v[224:227], v[10:13]
	v_mfma_f32_16x16x32_bf16 v[10:13], v[172:175], v[228:231], v[10:13]
	v_mfma_f32_16x16x32_bf16 v[54:57], v[176:179], v[192:195], v[54:57]
	v_mfma_f32_16x16x32_bf16 v[54:57], v[180:183], v[196:199], v[54:57]
	v_mfma_f32_16x16x32_bf16 v[50:53], v[184:187], v[192:195], v[50:53]
	v_mfma_f32_16x16x32_bf16 v[50:53], v[188:191], v[196:199], v[50:53]
	v_mfma_f32_16x16x32_bf16 v[38:41], v[176:179], v[200:203], v[38:41]
	v_mfma_f32_16x16x32_bf16 v[38:41], v[180:183], v[204:207], v[38:41]
	v_mfma_f32_16x16x32_bf16 v[34:37], v[184:187], v[200:203], v[34:37]
	v_mfma_f32_16x16x32_bf16 v[34:37], v[188:191], v[204:207], v[34:37]
	v_mfma_f32_16x16x32_bf16 v[22:25], v[176:179], v[216:219], v[22:25]
	v_mfma_f32_16x16x32_bf16 v[22:25], v[180:183], v[220:223], v[22:25]
	v_mfma_f32_16x16x32_bf16 v[18:21], v[184:187], v[216:219], v[18:21]
	v_mfma_f32_16x16x32_bf16 v[18:21], v[188:191], v[220:223], v[18:21]
	v_mfma_f32_16x16x32_bf16 v[6:9], v[176:179], v[224:227], v[6:9]
	v_mfma_f32_16x16x32_bf16 v[6:9], v[180:183], v[228:231], v[6:9]
	v_mfma_f32_16x16x32_bf16 v[2:5], v[184:187], v[224:227], v[2:5]
	v_mfma_f32_16x16x32_bf16 v[2:5], v[188:191], v[228:231], v[2:5]
	s_barrier
	s_add_i32 s29, s29, 2
	s_add_u32 s50, s50, 0x100
	s_addc_u32 s51, s51, 0
	s_add_u32 s17, s17, 0x100
	s_addc_u32 s23, s23, 0
	s_cmp_gt_u32 s29, 29
	s_cbranch_scc0 .LBB0_801
	s_and_b64 vcc, exec, s[20:21]
	s_cbranch_vccz .LBB0_804
	s_barrier

.Lsp_LBB01607:
	s_add_u32 s14, s64, 0xfff80080
	s_addc_u32 s15, s65, -1
	s_add_i32 s26, 0, 0x10000
	s_cmp_eq_u32 s25, 28
	s_cselect_b32 s67, s23, s15
	s_cselect_b32 s66, s22, s14
	v_add_u32_e32 v147, s26, v144
	s_cselect_b32 s15, s1, s24
	s_cselect_b32 s14, s10, s11
	s_add_i32 s28, 0, 0x14000
	ds_read_b128 v[140:143], v147
	ds_read_b128 v[148:151], v147 offset:1024
	ds_read_b128 v[152:155], v147 offset:2048
	ds_read_b128 v[168:171], v147 offset:3072
	v_add_u32_e32 v147, s28, v144
	ds_read_b128 v[172:175], v147
	ds_read_b128 v[176:179], v147 offset:1024
	ds_read_b128 v[180:183], v147 offset:2048
	ds_read_b128 v[184:187], v147 offset:3072
	v_lshl_add_u64 v[156:157], s[64:65], 0, v[136:137]
	s_add_i32 m0, s13, 0xc000
	ds_read_b128 v[188:191], v146
	ds_read_b128 v[192:195], v146 offset:1024
	ds_read_b128 v[196:199], v146 offset:2048
	ds_read_b128 v[200:203], v146 offset:3072
	ds_read_b128 v[204:207], v146 offset:4096
	ds_read_b128 v[216:219], v146 offset:5120
	ds_read_b128 v[220:223], v146 offset:6144
	ds_read_b128 v[224:227], v146 offset:7168
	global_load_lds_dwordx4 v[156:157], off
	v_lshl_add_u64 v[156:157], s[64:65], 0, v[138:139]
	s_add_i32 m0, s13, 0xe000
	s_nop 0
	global_load_lds_dwordx4 v[156:157], off
	s_waitcnt vmcnt(8)
	s_waitcnt lgkmcnt(0)
	s_barrier
	s_waitcnt lgkmcnt(0)
	v_mfma_f32_16x16x32_bf16 v[126:129], v[140:143], v[188:191], v[126:129]
	v_mfma_f32_16x16x32_bf16 v[126:129], v[148:151], v[192:195], v[126:129]
	v_mfma_f32_16x16x32_bf16 v[122:125], v[152:155], v[188:191], v[122:125]
	v_mfma_f32_16x16x32_bf16 v[122:125], v[168:171], v[192:195], v[122:125]
	v_mfma_f32_16x16x32_bf16 v[110:113], v[140:143], v[196:199], v[110:113]
	v_mfma_f32_16x16x32_bf16 v[110:113], v[148:151], v[200:203], v[110:113]
	v_mfma_f32_16x16x32_bf16 v[106:109], v[152:155], v[196:199], v[106:109]
	v_mfma_f32_16x16x32_bf16 v[106:109], v[168:171], v[200:203], v[106:109]
	v_mfma_f32_16x16x32_bf16 v[94:97], v[140:143], v[204:207], v[94:97]
	v_mfma_f32_16x16x32_bf16 v[94:97], v[148:151], v[216:219], v[94:97]
	v_mfma_f32_16x16x32_bf16 v[90:93], v[152:155], v[204:207], v[90:93]
	v_mfma_f32_16x16x32_bf16 v[90:93], v[168:171], v[216:219], v[90:93]
	v_mfma_f32_16x16x32_bf16 v[78:81], v[140:143], v[220:223], v[78:81]
	v_mfma_f32_16x16x32_bf16 v[78:81], v[148:151], v[224:227], v[78:81]
	v_mfma_f32_16x16x32_bf16 v[74:77], v[152:155], v[220:223], v[74:77]
	v_mfma_f32_16x16x32_bf16 v[74:77], v[168:171], v[224:227], v[74:77]
	v_mfma_f32_16x16x32_bf16 v[118:121], v[172:175], v[188:191], v[118:121]
	v_mfma_f32_16x16x32_bf16 v[118:121], v[176:179], v[192:195], v[118:121]
	v_mfma_f32_16x16x32_bf16 v[114:117], v[180:183], v[188:191], v[114:117]
	v_mfma_f32_16x16x32_bf16 v[114:117], v[184:187], v[192:195], v[114:117]
	v_mfma_f32_16x16x32_bf16 v[102:105], v[172:175], v[196:199], v[102:105]
	v_mfma_f32_16x16x32_bf16 v[102:105], v[176:179], v[200:203], v[102:105]
	v_mfma_f32_16x16x32_bf16 v[98:101], v[180:183], v[196:199], v[98:101]
	v_mfma_f32_16x16x32_bf16 v[98:101], v[184:187], v[200:203], v[98:101]
	v_mfma_f32_16x16x32_bf16 v[86:89], v[172:175], v[204:207], v[86:89]
	v_mfma_f32_16x16x32_bf16 v[86:89], v[176:179], v[216:219], v[86:89]
	v_mfma_f32_16x16x32_bf16 v[82:85], v[180:183], v[204:207], v[82:85]
	v_mfma_f32_16x16x32_bf16 v[82:85], v[184:187], v[216:219], v[82:85]
	v_mfma_f32_16x16x32_bf16 v[70:73], v[172:175], v[220:223], v[70:73]
	v_mfma_f32_16x16x32_bf16 v[70:73], v[176:179], v[224:227], v[70:73]
	v_mfma_f32_16x16x32_bf16 v[66:69], v[180:183], v[220:223], v[66:69]
	v_mfma_f32_16x16x32_bf16 v[66:69], v[184:187], v[224:227], v[66:69]
	s_barrier
	s_add_i32 s26, s26, s17
	v_lshl_add_u64 v[156:157], s[14:15], 0, v[158:159]
	s_mov_b32 m0, s26
	ds_read_b128 v[188:191], v146 offset:16384
	ds_read_b128 v[192:195], v146 offset:17408
	ds_read_b128 v[196:199], v146 offset:18432
	ds_read_b128 v[200:203], v146 offset:19456
	ds_read_b128 v[204:207], v146 offset:20480
	ds_read_b128 v[216:219], v146 offset:21504
	ds_read_b128 v[220:223], v146 offset:22528
	ds_read_b128 v[224:227], v146 offset:23552
	global_load_lds_dwordx4 v[156:157], off
	s_add_i32 m0, s26, 0x2000
	s_add_u32 s26, s14, 0x80000
	v_lshl_add_u64 v[228:229], s[14:15], 0, v[134:135]
	s_addc_u32 s27, s15, 0
	s_add_i32 s28, s28, s17
	global_load_lds_dwordx4 v[228:229], off
	v_lshl_add_u64 v[230:231], s[26:27], 0, v[158:159]
	s_mov_b32 m0, s28
	v_lshl_add_u64 v[232:233], s[66:67], 0, v[132:133]
	global_load_lds_dwordx4 v[230:231], off
	v_lshl_add_u64 v[230:231], s[26:27], 0, v[134:135]
	s_add_i32 m0, s28, 0x2000
	s_nop 0
	global_load_lds_dwordx4 v[230:231], off
	v_lshl_add_u64 v[230:231], s[66:67], 0, v[130:131]
	s_mov_b32 m0, s13
	s_nop 0
	global_load_lds_dwordx4 v[230:231], off
	s_mov_b32 m0, s53
	s_nop 0
	global_load_lds_dwordx4 v[232:233], off
	s_waitcnt vmcnt(8)
	s_waitcnt lgkmcnt(0)
	s_barrier
	s_waitcnt lgkmcnt(0)
	v_mfma_f32_16x16x32_bf16 v[62:65], v[140:143], v[188:191], v[62:65]
	v_mfma_f32_16x16x32_bf16 v[62:65], v[148:151], v[192:195], v[62:65]
	v_mfma_f32_16x16x32_bf16 v[58:61], v[152:155], v[188:191], v[58:61]
	v_mfma_f32_16x16x32_bf16 v[58:61], v[168:171], v[192:195], v[58:61]
	v_mfma_f32_16x16x32_bf16 v[46:49], v[140:143], v[196:199], v[46:49]
	v_mfma_f32_16x16x32_bf16 v[46:49], v[148:151], v[200:203], v[46:49]
	v_mfma_f32_16x16x32_bf16 v[42:45], v[152:155], v[196:199], v[42:45]
	v_mfma_f32_16x16x32_bf16 v[42:45], v[168:171], v[200:203], v[42:45]
	v_mfma_f32_16x16x32_bf16 v[30:33], v[140:143], v[204:207], v[30:33]
	v_mfma_f32_16x16x32_bf16 v[30:33], v[148:151], v[216:219], v[30:33]
	v_mfma_f32_16x16x32_bf16 v[26:29], v[152:155], v[204:207], v[26:29]
	v_mfma_f32_16x16x32_bf16 v[26:29], v[168:171], v[216:219], v[26:29]
	v_mfma_f32_16x16x32_bf16 v[14:17], v[140:143], v[220:223], v[14:17]
	v_mfma_f32_16x16x32_bf16 v[14:17], v[148:151], v[224:227], v[14:17]
	v_mfma_f32_16x16x32_bf16 v[10:13], v[152:155], v[220:223], v[10:13]
	v_mfma_f32_16x16x32_bf16 v[10:13], v[168:171], v[224:227], v[10:13]
	v_mfma_f32_16x16x32_bf16 v[54:57], v[172:175], v[188:191], v[54:57]
	v_mfma_f32_16x16x32_bf16 v[54:57], v[176:179], v[192:195], v[54:57]
	v_mfma_f32_16x16x32_bf16 v[50:53], v[180:183], v[188:191], v[50:53]
	v_mfma_f32_16x16x32_bf16 v[50:53], v[184:187], v[192:195], v[50:53]
	v_mfma_f32_16x16x32_bf16 v[38:41], v[172:175], v[196:199], v[38:41]
	v_mfma_f32_16x16x32_bf16 v[38:41], v[176:179], v[200:203], v[38:41]
	v_mfma_f32_16x16x32_bf16 v[34:37], v[180:183], v[196:199], v[34:37]
	v_mfma_f32_16x16x32_bf16 v[34:37], v[184:187], v[200:203], v[34:37]
	v_mfma_f32_16x16x32_bf16 v[22:25], v[172:175], v[204:207], v[22:25]
	v_mfma_f32_16x16x32_bf16 v[22:25], v[176:179], v[216:219], v[22:25]
	v_mfma_f32_16x16x32_bf16 v[18:21], v[180:183], v[204:207], v[18:21]
	v_mfma_f32_16x16x32_bf16 v[18:21], v[184:187], v[216:219], v[18:21]
	v_mfma_f32_16x16x32_bf16 v[6:9], v[172:175], v[220:223], v[6:9]
	v_mfma_f32_16x16x32_bf16 v[6:9], v[176:179], v[224:227], v[6:9]
	v_mfma_f32_16x16x32_bf16 v[2:5], v[180:183], v[220:223], v[2:5]
	v_mfma_f32_16x16x32_bf16 v[2:5], v[184:187], v[224:227], v[2:5]
	s_barrier
	s_add_i32 s28, 0, 0x18000
	v_add_u32_e32 v147, s28, v144
	s_add_i32 s29, 0, 0x1c000
	ds_read_b128 v[140:143], v147
	ds_read_b128 v[148:151], v147 offset:1024
	ds_read_b128 v[152:155], v147 offset:2048
	ds_read_b128 v[168:171], v147 offset:3072
	v_add_u32_e32 v147, s29, v144
	ds_read_b128 v[172:175], v147
	ds_read_b128 v[176:179], v147 offset:1024
	ds_read_b128 v[180:183], v147 offset:2048
	ds_read_b128 v[184:187], v147 offset:3072
	s_add_u32 s26, s66, 0x80000
	s_addc_u32 s27, s67, 0
	s_mov_b32 m0, s58
	v_lshl_add_u64 v[234:235], s[26:27], 0, v[130:131]
	ds_read_b128 v[188:191], v146 offset:32768
	ds_read_b128 v[192:195], v146 offset:33792
	ds_read_b128 v[196:199], v146 offset:34816
	ds_read_b128 v[200:203], v146 offset:35840
	ds_read_b128 v[204:207], v146 offset:36864
	ds_read_b128 v[216:219], v146 offset:37888
	ds_read_b128 v[220:223], v146 offset:38912
	ds_read_b128 v[224:227], v146 offset:39936
	global_load_lds_dwordx4 v[234:235], off
	v_lshl_add_u64 v[234:235], s[26:27], 0, v[132:133]
	s_mov_b32 m0, s59
	s_nop 0
	global_load_lds_dwordx4 v[234:235], off
	s_waitcnt vmcnt(8)
	s_waitcnt lgkmcnt(0)
	s_barrier
	s_waitcnt lgkmcnt(0)
	v_mfma_f32_16x16x32_bf16 v[126:129], v[140:143], v[188:191], v[126:129]
	v_mfma_f32_16x16x32_bf16 v[126:129], v[148:151], v[192:195], v[126:129]
	v_mfma_f32_16x16x32_bf16 v[122:125], v[152:155], v[188:191], v[122:125]
	v_mfma_f32_16x16x32_bf16 v[122:125], v[168:171], v[192:195], v[122:125]
	v_mfma_f32_16x16x32_bf16 v[110:113], v[140:143], v[196:199], v[110:113]
	v_mfma_f32_16x16x32_bf16 v[110:113], v[148:151], v[200:203], v[110:113]
	v_mfma_f32_16x16x32_bf16 v[106:109], v[152:155], v[196:199], v[106:109]
	v_mfma_f32_16x16x32_bf16 v[106:109], v[168:171], v[200:203], v[106:109]
	v_mfma_f32_16x16x32_bf16 v[94:97], v[140:143], v[204:207], v[94:97]
	v_mfma_f32_16x16x32_bf16 v[94:97], v[148:151], v[216:219], v[94:97]
	v_mfma_f32_16x16x32_bf16 v[90:93], v[152:155], v[204:207], v[90:93]
	v_mfma_f32_16x16x32_bf16 v[90:93], v[168:171], v[216:219], v[90:93]
	v_mfma_f32_16x16x32_bf16 v[78:81], v[140:143], v[220:223], v[78:81]
	v_mfma_f32_16x16x32_bf16 v[78:81], v[148:151], v[224:227], v[78:81]
	v_mfma_f32_16x16x32_bf16 v[74:77], v[152:155], v[220:223], v[74:77]
	v_mfma_f32_16x16x32_bf16 v[74:77], v[168:171], v[224:227], v[74:77]
	v_mfma_f32_16x16x32_bf16 v[118:121], v[172:175], v[188:191], v[118:121]
	v_mfma_f32_16x16x32_bf16 v[118:121], v[176:179], v[192:195], v[118:121]
	v_mfma_f32_16x16x32_bf16 v[114:117], v[180:183], v[188:191], v[114:117]
	v_mfma_f32_16x16x32_bf16 v[114:117], v[184:187], v[192:195], v[114:117]
	v_mfma_f32_16x16x32_bf16 v[102:105], v[172:175], v[196:199], v[102:105]
	v_mfma_f32_16x16x32_bf16 v[102:105], v[176:179], v[200:203], v[102:105]
	v_mfma_f32_16x16x32_bf16 v[98:101], v[180:183], v[196:199], v[98:101]
	v_mfma_f32_16x16x32_bf16 v[98:101], v[184:187], v[200:203], v[98:101]
	v_mfma_f32_16x16x32_bf16 v[86:89], v[172:175], v[204:207], v[86:89]
	v_mfma_f32_16x16x32_bf16 v[86:89], v[176:179], v[216:219], v[86:89]
	v_mfma_f32_16x16x32_bf16 v[82:85], v[180:183], v[204:207], v[82:85]
	v_mfma_f32_16x16x32_bf16 v[82:85], v[184:187], v[216:219], v[82:85]
	v_mfma_f32_16x16x32_bf16 v[70:73], v[172:175], v[220:223], v[70:73]
	v_mfma_f32_16x16x32_bf16 v[70:73], v[176:179], v[224:227], v[70:73]
	v_mfma_f32_16x16x32_bf16 v[66:69], v[180:183], v[220:223], v[66:69]
	v_mfma_f32_16x16x32_bf16 v[66:69], v[184:187], v[224:227], v[66:69]
	s_barrier
	s_add_i32 s26, s28, s17
	v_lshl_add_u64 v[156:157], v[156:157], 0, s[56:57]
	s_mov_b32 m0, s26
	ds_read_b128 v[188:191], v146 offset:49152
	ds_read_b128 v[192:195], v146 offset:50176
	ds_read_b128 v[196:199], v146 offset:51200
	ds_read_b128 v[200:203], v146 offset:52224
	ds_read_b128 v[204:207], v146 offset:53248
	ds_read_b128 v[216:219], v146 offset:54272
	ds_read_b128 v[220:223], v146 offset:55296
	ds_read_b128 v[224:227], v146 offset:56320
	global_load_lds_dwordx4 v[156:157], off
	s_add_i32 m0, s26, 0x2000
	s_add_u32 s14, s14, 0x80080
	v_lshl_add_u64 v[156:157], v[228:229], 0, s[56:57]
	s_addc_u32 s15, s15, 0
	s_add_i32 s26, s29, s17
	global_load_lds_dwordx4 v[156:157], off
	v_lshl_add_u64 v[156:157], s[14:15], 0, v[158:159]
	s_mov_b32 m0, s26
	s_nop 0
	global_load_lds_dwordx4 v[156:157], off
	v_lshl_add_u64 v[156:157], s[14:15], 0, v[134:135]
	s_add_i32 m0, s26, 0x2000
	s_nop 0
	global_load_lds_dwordx4 v[156:157], off
	v_lshl_add_u64 v[156:157], v[230:231], 0, s[56:57]
	s_mov_b32 m0, s54
	s_nop 0
	global_load_lds_dwordx4 v[156:157], off
	v_lshl_add_u64 v[156:157], v[232:233], 0, s[56:57]
	s_mov_b32 m0, s68
	s_nop 0
	global_load_lds_dwordx4 v[156:157], off
	s_waitcnt vmcnt(8)
	s_waitcnt lgkmcnt(0)
	s_barrier
	s_waitcnt lgkmcnt(0)
	v_mfma_f32_16x16x32_bf16 v[62:65], v[140:143], v[188:191], v[62:65]
	v_mfma_f32_16x16x32_bf16 v[62:65], v[148:151], v[192:195], v[62:65]
	v_mfma_f32_16x16x32_bf16 v[58:61], v[152:155], v[188:191], v[58:61]
	v_mfma_f32_16x16x32_bf16 v[58:61], v[168:171], v[192:195], v[58:61]
	v_mfma_f32_16x16x32_bf16 v[46:49], v[140:143], v[196:199], v[46:49]
	v_mfma_f32_16x16x32_bf16 v[46:49], v[148:151], v[200:203], v[46:49]
	v_mfma_f32_16x16x32_bf16 v[42:45], v[152:155], v[196:199], v[42:45]
	v_mfma_f32_16x16x32_bf16 v[42:45], v[168:171], v[200:203], v[42:45]
	v_mfma_f32_16x16x32_bf16 v[30:33], v[140:143], v[204:207], v[30:33]
	v_mfma_f32_16x16x32_bf16 v[30:33], v[148:151], v[216:219], v[30:33]
	v_mfma_f32_16x16x32_bf16 v[26:29], v[152:155], v[204:207], v[26:29]
	v_mfma_f32_16x16x32_bf16 v[26:29], v[168:171], v[216:219], v[26:29]
	v_mfma_f32_16x16x32_bf16 v[14:17], v[140:143], v[220:223], v[14:17]
	v_mfma_f32_16x16x32_bf16 v[14:17], v[148:151], v[224:227], v[14:17]
	v_mfma_f32_16x16x32_bf16 v[10:13], v[152:155], v[220:223], v[10:13]
	v_mfma_f32_16x16x32_bf16 v[10:13], v[168:171], v[224:227], v[10:13]
	v_mfma_f32_16x16x32_bf16 v[54:57], v[172:175], v[188:191], v[54:57]
	v_mfma_f32_16x16x32_bf16 v[54:57], v[176:179], v[192:195], v[54:57]
	v_mfma_f32_16x16x32_bf16 v[50:53], v[180:183], v[188:191], v[50:53]
	v_mfma_f32_16x16x32_bf16 v[50:53], v[184:187], v[192:195], v[50:53]
	v_mfma_f32_16x16x32_bf16 v[38:41], v[172:175], v[196:199], v[38:41]
	v_mfma_f32_16x16x32_bf16 v[38:41], v[176:179], v[200:203], v[38:41]
	v_mfma_f32_16x16x32_bf16 v[34:37], v[180:183], v[196:199], v[34:37]
	v_mfma_f32_16x16x32_bf16 v[34:37], v[184:187], v[200:203], v[34:37]
	v_mfma_f32_16x16x32_bf16 v[22:25], v[172:175], v[204:207], v[22:25]
	v_mfma_f32_16x16x32_bf16 v[22:25], v[176:179], v[216:219], v[22:25]
	v_mfma_f32_16x16x32_bf16 v[18:21], v[180:183], v[204:207], v[18:21]
	v_mfma_f32_16x16x32_bf16 v[18:21], v[184:187], v[216:219], v[18:21]
	v_mfma_f32_16x16x32_bf16 v[6:9], v[172:175], v[220:223], v[6:9]
	v_mfma_f32_16x16x32_bf16 v[6:9], v[176:179], v[224:227], v[6:9]
	v_mfma_f32_16x16x32_bf16 v[2:5], v[180:183], v[220:223], v[2:5]
	v_mfma_f32_16x16x32_bf16 v[2:5], v[184:187], v[224:227], v[2:5]
	s_barrier
	s_add_i32 s25, s25, 2
	s_add_u32 s64, s64, 0x100
	s_addc_u32 s65, s65, 0
	s_add_u32 s11, s11, 0x100
	s_addc_u32 s24, s24, 0
	s_cmp_gt_u32 s25, 29
	s_cbranch_scc0 .LBB0_1607
	s_and_b64 vcc, exec, s[42:43]
	s_cbranch_vccz .LBB0_1610
	s_barrier
